# v21: v18 + memory cross-attention unit (ph5/13): K and V LDS fragments go through a ring of free VGPR quads with counted waits instead of read/wait(0)/MFMA per fragment
# speedup vs baseline: 1.0009x; 1.0009x over previous
.LBB0_489:
	s_or_b64 exec, exec, s[48:49]
	v_cvt_pk_bf16_f32 v122, v121, v122
	v_cvt_pk_bf16_f32 v121, v104, v105
	v_cvt_pk_bf16_f32 v104, v70, v71
	v_cvt_pk_bf16_f32 v70, v2, v3
	v_lshlrev_b32_e32 v2, 1, v204
	v_readlane_b32 s38, v251, 37
	v_cvt_pk_bf16_f32 v123, v123, v124
	v_cvt_pk_bf16_f32 v124, v125, v130
	v_cvt_pk_bf16_f32 v71, v4, v5
	v_and_b32_e32 v4, 2, v2
	v_lshlrev_b32_e32 v2, 3, v195
	v_lshl_add_u32 v130, v202, 4, s38
	s_mov_b64 s[38:39], 0x900
	v_cvt_pk_bf16_f32 v105, v72, v73
	v_cvt_pk_bf16_f32 v72, v6, v7
	v_and_b32_e32 v6, 8, v2
	v_lshl_add_u64 v[2:3], v[196:197], 0, s[38:39]
	s_mov_b32 s38, m0
	s_mov_b32 m0, s0
	s_nop 0
	global_load_lds_dwordx4 v[2:3], off
	s_mov_b32 m0, s38
	s_mov_b64 s[38:39], 0x20900
	v_lshl_add_u64 v[2:3], v[196:197], 0, s[38:39]
	s_mov_b32 s38, m0
	s_mov_b32 m0, s22
	s_nop 0
	global_load_lds_dwordx4 v[2:3], off
	s_mov_b32 m0, s38
	s_mov_b64 s[38:39], 0x40900
	v_lshl_add_u64 v[2:3], v[196:197], 0, s[38:39]
	s_mov_b32 s22, m0
	s_mov_b32 m0, s23
	s_nop 0
	global_load_lds_dwordx4 v[2:3], off
	s_mov_b32 m0, s22
	v_lshlrev_b32_e32 v133, 2, v202
	v_lshrrev_b32_e32 v126, 2, v205
	s_mov_b64 s[22:23], 0x60900
	v_or_b32_e32 v134, v133, v126
	v_bfe_u32 v5, v195, 1, 1
	v_lshl_add_u64 v[2:3], v[196:197], 0, s[22:23]
	s_waitcnt lgkmcnt(0)
	v_cvt_pk_bf16_f32 v127, v115, v116
	v_cvt_pk_bf16_f32 v115, v108, v109
	v_cvt_pk_bf16_f32 v108, v94, v95
	v_cvt_pk_bf16_f32 v94, v50, v51
	v_or_b32_e32 v50, v4, v5
	s_mov_b32 s22, m0
	s_mov_b32 m0, s26
	s_nop 0
	global_load_lds_dwordx4 v[2:3], off
	s_mov_b32 m0, s22
	v_bitop3_b32 v2, v4, v134, v5 bitop3:0x36
	v_cvt_pk_bf16_f32 v128, v117, v118
	v_cvt_pk_bf16_f32 v129, v119, v120
	v_cvt_pk_bf16_f32 v119, v100, v101
	v_cvt_pk_bf16_f32 v117, v112, v113
	v_cvt_pk_bf16_f32 v112, v86, v87
	v_cvt_pk_bf16_f32 v100, v78, v79
	v_cvt_pk_bf16_f32 v86, v34, v35
	v_cvt_pk_bf16_f32 v78, v18, v19
	v_lshlrev_b32_e32 v135, 4, v2
	v_lshlrev_b32_e32 v2, 8, v134
	v_bitop3_b32 v18, v50, v134, 4 bitop3:0x36
	v_bitop3_b32 v34, v50, v134, 8 bitop3:0x36
	v_bitop3_b32 v50, v50, v134, 12 bitop3:0x36
	v_add3_u32 v136, 0, v6, v2
	v_lshlrev_b32_e32 v137, 4, v18
	v_lshlrev_b32_e32 v138, 4, v34
	v_lshlrev_b32_e32 v139, 4, v50
	v_cvt_pk_bf16_f32 v126, v0, v114
	v_cvt_pk_bf16_f32 v125, v131, v132
	v_add_u32_e32 v0, s42, v133
	v_add_u32_e32 v131, v136, v135
	v_add_u32_e32 v132, v136, v137
	v_add_u32_e32 v133, v136, v138
	v_add_u32_e32 v134, v136, v139
	v_cvt_pk_bf16_f32 v95, v52, v53
	v_cvt_pk_bf16_f32 v87, v36, v37
	v_cvt_pk_bf16_f32 v79, v20, v21
	ds_read_b64_tr_b16 v[2:3], v131 offset:32768
	ds_read_b64_tr_b16 v[4:5], v131 offset:34816
	ds_read_b64_tr_b16 v[18:19], v132 offset:32768
	ds_read_b64_tr_b16 v[20:21], v132 offset:34816
	ds_read_b64_tr_b16 v[34:35], v133 offset:32768
	ds_read_b64_tr_b16 v[36:37], v133 offset:34816
	ds_read_b64_tr_b16 v[50:51], v134 offset:32768
	ds_read_b64_tr_b16 v[52:53], v134 offset:34816
	v_lshl_add_u32 v0, v0, 10, s44
	v_cvt_pk_bf16_f32 v118, v98, v99
	v_cvt_pk_bf16_f32 v120, v102, v103
	v_cvt_pk_bf16_f32 v114, v106, v107
	v_cvt_pk_bf16_f32 v116, v110, v111
	v_cvt_pk_bf16_f32 v110, v82, v83
	v_cvt_pk_bf16_f32 v111, v84, v85
	v_cvt_pk_bf16_f32 v113, v88, v89
	v_cvt_pk_bf16_f32 v106, v90, v91
	v_cvt_pk_bf16_f32 v107, v92, v93
	v_cvt_pk_bf16_f32 v109, v96, v97
	v_cvt_pk_bf16_f32 v102, v66, v67
	v_cvt_pk_bf16_f32 v103, v68, v69
	v_cvt_pk_bf16_f32 v98, v74, v75
	v_cvt_pk_bf16_f32 v99, v76, v77
	v_cvt_pk_bf16_f32 v101, v80, v81
	v_cvt_pk_bf16_f32 v96, v54, v55
	v_cvt_pk_bf16_f32 v97, v56, v57
	v_cvt_pk_bf16_f32 v90, v58, v59
	v_cvt_pk_bf16_f32 v91, v60, v61
	v_cvt_pk_bf16_f32 v92, v62, v63
	v_cvt_pk_bf16_f32 v93, v64, v65
	v_cvt_pk_bf16_f32 v88, v38, v39
	v_cvt_pk_bf16_f32 v89, v40, v41
	v_cvt_pk_bf16_f32 v82, v42, v43
	v_cvt_pk_bf16_f32 v83, v44, v45
	v_cvt_pk_bf16_f32 v84, v46, v47
	v_cvt_pk_bf16_f32 v85, v48, v49
	v_cvt_pk_bf16_f32 v80, v22, v23
	v_cvt_pk_bf16_f32 v81, v24, v25
	v_cvt_pk_bf16_f32 v74, v26, v27
	v_cvt_pk_bf16_f32 v75, v28, v29
	v_cvt_pk_bf16_f32 v76, v30, v31
	v_cvt_pk_bf16_f32 v77, v32, v33
	v_cvt_pk_bf16_f32 v73, v8, v9
	v_cvt_pk_bf16_f32 v66, v10, v11
	v_cvt_pk_bf16_f32 v67, v12, v13
	v_cvt_pk_bf16_f32 v68, v14, v15
	v_cvt_pk_bf16_f32 v69, v16, v17
	v_or_b32_e32 v0, v0, v203
	s_waitcnt lgkmcnt(6)
	v_mfma_f32_32x32x16_bf16 v[2:17], v[126:129], v[2:5], 0
	s_waitcnt lgkmcnt(4)
	v_mfma_f32_32x32x16_bf16 v[18:33], v[126:129], v[18:21], 0
	s_waitcnt lgkmcnt(2)
	v_mfma_f32_32x32x16_bf16 v[34:49], v[126:129], v[34:37], 0
	s_waitcnt lgkmcnt(0)
	v_mfma_f32_32x32x16_bf16 v[50:65], v[126:129], v[50:53], 0
	ds_read_b64_tr_b16 v[154:155], v131 offset:36864
	ds_read_b64_tr_b16 v[156:157], v131 offset:38912
	ds_read_b64_tr_b16 v[158:159], v132 offset:36864
	ds_read_b64_tr_b16 v[160:161], v132 offset:38912
	ds_read_b64_tr_b16 v[162:163], v133 offset:36864
	ds_read_b64_tr_b16 v[164:165], v133 offset:38912
	ds_read_b64_tr_b16 v[166:167], v134 offset:36864
	ds_read_b64_tr_b16 v[168:169], v134 offset:38912
	ds_read_b64_tr_b16 v[170:171], v131 offset:40960
	ds_read_b64_tr_b16 v[172:173], v131 offset:43008
	ds_read_b64_tr_b16 v[174:175], v132 offset:40960
	ds_read_b64_tr_b16 v[176:177], v132 offset:43008
	ds_read_b64_tr_b16 v[178:179], v133 offset:40960
	ds_read_b64_tr_b16 v[180:181], v133 offset:43008
	ds_read_b64_tr_b16 v[182:183], v134 offset:40960
	ds_read_b64_tr_b16 v[184:185], v134 offset:43008
	s_waitcnt lgkmcnt(14)
	v_mfma_f32_32x32x16_bf16 v[2:17], v[122:125], v[154:157], v[2:17]
	ds_read_b64_tr_b16 v[154:155], v131 offset:45056
	ds_read_b64_tr_b16 v[156:157], v131 offset:47104
	s_waitcnt lgkmcnt(14)
	v_mfma_f32_32x32x16_bf16 v[18:33], v[122:125], v[158:161], v[18:33]
	ds_read_b64_tr_b16 v[158:159], v132 offset:45056
	ds_read_b64_tr_b16 v[160:161], v132 offset:47104
	s_waitcnt lgkmcnt(14)
	v_mfma_f32_32x32x16_bf16 v[34:49], v[122:125], v[162:165], v[34:49]
	ds_read_b64_tr_b16 v[162:163], v133 offset:45056
	ds_read_b64_tr_b16 v[164:165], v133 offset:47104
	s_waitcnt lgkmcnt(14)
	v_mfma_f32_32x32x16_bf16 v[50:65], v[122:125], v[166:169], v[50:65]
	ds_read_b64_tr_b16 v[166:167], v134 offset:45056
	ds_read_b64_tr_b16 v[168:169], v134 offset:47104
	s_waitcnt lgkmcnt(14)
	v_mfma_f32_32x32x16_bf16 v[2:17], v[118:121], v[170:173], v[2:17]
	ds_read_b64_tr_b16 v[170:171], v131 offset:49152
	ds_read_b64_tr_b16 v[172:173], v131 offset:51200
	s_waitcnt lgkmcnt(14)
	v_mfma_f32_32x32x16_bf16 v[18:33], v[118:121], v[174:177], v[18:33]
	ds_read_b64_tr_b16 v[174:175], v132 offset:49152
	ds_read_b64_tr_b16 v[176:177], v132 offset:51200
	s_waitcnt lgkmcnt(14)
	v_mfma_f32_32x32x16_bf16 v[34:49], v[118:121], v[178:181], v[34:49]
	ds_read_b64_tr_b16 v[178:179], v133 offset:49152
	ds_read_b64_tr_b16 v[180:181], v133 offset:51200
	s_waitcnt lgkmcnt(14)
	v_mfma_f32_32x32x16_bf16 v[50:65], v[118:121], v[182:185], v[50:65]
	ds_read_b64_tr_b16 v[182:183], v134 offset:49152
	ds_read_b64_tr_b16 v[184:185], v134 offset:51200
	s_waitcnt lgkmcnt(14)
	v_mfma_f32_32x32x16_bf16 v[2:17], v[114:117], v[154:157], v[2:17]
	ds_read_b64_tr_b16 v[154:155], v131 offset:53248
	ds_read_b64_tr_b16 v[156:157], v131 offset:55296
	s_waitcnt lgkmcnt(14)
	v_mfma_f32_32x32x16_bf16 v[18:33], v[114:117], v[158:161], v[18:33]
	ds_read_b64_tr_b16 v[158:159], v132 offset:53248
	ds_read_b64_tr_b16 v[160:161], v132 offset:55296
	s_waitcnt lgkmcnt(14)
	v_mfma_f32_32x32x16_bf16 v[34:49], v[114:117], v[162:165], v[34:49]
	ds_read_b64_tr_b16 v[162:163], v133 offset:53248
	ds_read_b64_tr_b16 v[164:165], v133 offset:55296
	s_waitcnt lgkmcnt(14)
	v_mfma_f32_32x32x16_bf16 v[50:65], v[114:117], v[166:169], v[50:65]
	ds_read_b64_tr_b16 v[166:167], v134 offset:53248
	ds_read_b64_tr_b16 v[168:169], v134 offset:55296
	s_waitcnt lgkmcnt(14)
	v_mfma_f32_32x32x16_bf16 v[2:17], v[110:113], v[170:173], v[2:17]
	ds_read_b64_tr_b16 v[170:171], v131 offset:57344
	ds_read_b64_tr_b16 v[172:173], v131 offset:59392
	s_waitcnt lgkmcnt(14)
	v_mfma_f32_32x32x16_bf16 v[18:33], v[110:113], v[174:177], v[18:33]
	ds_read_b64_tr_b16 v[174:175], v132 offset:57344
	ds_read_b64_tr_b16 v[176:177], v132 offset:59392
	s_waitcnt lgkmcnt(14)
	v_mfma_f32_32x32x16_bf16 v[34:49], v[110:113], v[178:181], v[34:49]
	ds_read_b64_tr_b16 v[178:179], v133 offset:57344
	ds_read_b64_tr_b16 v[180:181], v133 offset:59392
	s_waitcnt lgkmcnt(14)
	v_mfma_f32_32x32x16_bf16 v[50:65], v[110:113], v[182:185], v[50:65]
	ds_read_b64_tr_b16 v[182:183], v134 offset:57344
	ds_read_b64_tr_b16 v[184:185], v134 offset:59392
	s_waitcnt lgkmcnt(14)
	v_mfma_f32_32x32x16_bf16 v[2:17], v[106:109], v[154:157], v[2:17]
	ds_read_b64_tr_b16 v[154:155], v131 offset:61440
	ds_read_b64_tr_b16 v[156:157], v131 offset:63488
	s_waitcnt lgkmcnt(14)
	v_mfma_f32_32x32x16_bf16 v[18:33], v[106:109], v[158:161], v[18:33]
	ds_read_b64_tr_b16 v[158:159], v132 offset:61440
	ds_read_b64_tr_b16 v[160:161], v132 offset:63488
	s_waitcnt lgkmcnt(14)
	v_mfma_f32_32x32x16_bf16 v[34:49], v[106:109], v[162:165], v[34:49]
	ds_read_b64_tr_b16 v[162:163], v133 offset:61440
	ds_read_b64_tr_b16 v[164:165], v133 offset:63488
	s_waitcnt lgkmcnt(14)
	v_mfma_f32_32x32x16_bf16 v[50:65], v[106:109], v[166:169], v[50:65]
	ds_read_b64_tr_b16 v[166:167], v134 offset:61440
	ds_read_b64_tr_b16 v[168:169], v134 offset:63488
	s_waitcnt lgkmcnt(14)
	v_mfma_f32_32x32x16_bf16 v[2:17], v[102:105], v[170:173], v[2:17]
	s_waitcnt lgkmcnt(12)
	v_mfma_f32_32x32x16_bf16 v[18:33], v[102:105], v[174:177], v[18:33]
	s_waitcnt lgkmcnt(10)
	v_mfma_f32_32x32x16_bf16 v[34:49], v[102:105], v[178:181], v[34:49]
	s_waitcnt lgkmcnt(8)
	v_mfma_f32_32x32x16_bf16 v[50:65], v[102:105], v[182:185], v[50:65]
	s_waitcnt lgkmcnt(6)
	v_mfma_f32_32x32x16_bf16 v[2:17], v[98:101], v[154:157], v[2:17]
	s_waitcnt lgkmcnt(4)
	v_mfma_f32_32x32x16_bf16 v[18:33], v[98:101], v[158:161], v[18:33]
	s_waitcnt lgkmcnt(2)
	v_mfma_f32_32x32x16_bf16 v[34:49], v[98:101], v[162:165], v[34:49]
	s_waitcnt lgkmcnt(0)
	v_mfma_f32_32x32x16_bf16 v[50:65], v[98:101], v[166:169], v[50:65]
	s_waitcnt vmcnt(4) lgkmcnt(0)
	s_barrier
	s_mov_b64 s[22:23], 0x80900
	v_lshl_add_u64 v[140:141], v[196:197], 0, s[22:23]
	s_mov_b32 s22, m0
	s_mov_b32 m0, s27
	s_nop 0
	global_load_lds_dwordx4 v[140:141], off
	s_mov_b32 m0, s22
	s_mov_b64 s[22:23], 0xa0900
	v_lshl_add_u64 v[140:141], v[196:197], 0, s[22:23]
	s_mov_b32 s22, m0
	s_mov_b32 m0, s9
	s_nop 0
	global_load_lds_dwordx4 v[140:141], off
	s_mov_b32 m0, s22
	s_mov_b64 s[22:23], 0xc0900
	v_lshl_add_u64 v[140:141], v[196:197], 0, s[22:23]
	s_mov_b32 s9, m0
	s_mov_b32 m0, s10
	s_nop 0
	global_load_lds_dwordx4 v[140:141], off
	s_mov_b32 m0, s9
	s_mov_b64 s[22:23], 0xe0900
	v_add_u32_e32 v144, 0x10000, v136
	v_lshl_add_u64 v[140:141], v[196:197], 0, s[22:23]
	s_mov_b32 s9, m0
	s_mov_b32 m0, s11
	s_nop 0
	global_load_lds_dwordx4 v[140:141], off
	s_mov_b32 m0, s9
	v_add_u32_e32 v186, 0x10000, v131
	v_add_u32_e32 v187, 0x10000, v132
	v_add_u32_e32 v188, 0x10000, v133
	v_add_u32_e32 v189, 0x10000, v134
	ds_read_b64_tr_b16 v[154:155], v186 offset:0
	ds_read_b64_tr_b16 v[156:157], v186 offset:2048
	ds_read_b64_tr_b16 v[158:159], v187 offset:0
	ds_read_b64_tr_b16 v[160:161], v187 offset:2048
	ds_read_b64_tr_b16 v[162:163], v188 offset:0
	ds_read_b64_tr_b16 v[164:165], v188 offset:2048
	ds_read_b64_tr_b16 v[166:167], v189 offset:0
	ds_read_b64_tr_b16 v[168:169], v189 offset:2048
	ds_read_b64_tr_b16 v[170:171], v186 offset:4096
	ds_read_b64_tr_b16 v[172:173], v186 offset:6144
	ds_read_b64_tr_b16 v[174:175], v187 offset:4096
	ds_read_b64_tr_b16 v[176:177], v187 offset:6144
	ds_read_b64_tr_b16 v[178:179], v188 offset:4096
	ds_read_b64_tr_b16 v[180:181], v188 offset:6144
	ds_read_b64_tr_b16 v[182:183], v189 offset:4096
	ds_read_b64_tr_b16 v[184:185], v189 offset:6144
	s_waitcnt lgkmcnt(14)
	v_mfma_f32_32x32x16_bf16 v[2:17], v[94:97], v[154:157], v[2:17]
	ds_read_b64_tr_b16 v[154:155], v186 offset:8192
	ds_read_b64_tr_b16 v[156:157], v186 offset:10240
	s_waitcnt lgkmcnt(14)
	v_mfma_f32_32x32x16_bf16 v[18:33], v[94:97], v[158:161], v[18:33]
	ds_read_b64_tr_b16 v[158:159], v187 offset:8192
	ds_read_b64_tr_b16 v[160:161], v187 offset:10240
	s_waitcnt lgkmcnt(14)
	v_mfma_f32_32x32x16_bf16 v[34:49], v[94:97], v[162:165], v[34:49]
	ds_read_b64_tr_b16 v[162:163], v188 offset:8192
	ds_read_b64_tr_b16 v[164:165], v188 offset:10240
	s_waitcnt lgkmcnt(14)
	v_mfma_f32_32x32x16_bf16 v[50:65], v[94:97], v[166:169], v[50:65]
	ds_read_b64_tr_b16 v[166:167], v189 offset:8192
	ds_read_b64_tr_b16 v[168:169], v189 offset:10240
	s_waitcnt lgkmcnt(14)
	v_mfma_f32_32x32x16_bf16 v[2:17], v[90:93], v[170:173], v[2:17]
	ds_read_b64_tr_b16 v[170:171], v186 offset:12288
	ds_read_b64_tr_b16 v[172:173], v186 offset:14336
	s_waitcnt lgkmcnt(14)
	v_mfma_f32_32x32x16_bf16 v[18:33], v[90:93], v[174:177], v[18:33]
	ds_read_b64_tr_b16 v[174:175], v187 offset:12288
	ds_read_b64_tr_b16 v[176:177], v187 offset:14336
	s_waitcnt lgkmcnt(14)
	v_mfma_f32_32x32x16_bf16 v[34:49], v[90:93], v[178:181], v[34:49]
	ds_read_b64_tr_b16 v[178:179], v188 offset:12288
	ds_read_b64_tr_b16 v[180:181], v188 offset:14336
	s_waitcnt lgkmcnt(14)
	v_mfma_f32_32x32x16_bf16 v[50:65], v[90:93], v[182:185], v[50:65]
	ds_read_b64_tr_b16 v[182:183], v189 offset:12288
	ds_read_b64_tr_b16 v[184:185], v189 offset:14336
	s_waitcnt lgkmcnt(14)
	v_mfma_f32_32x32x16_bf16 v[2:17], v[86:89], v[154:157], v[2:17]
	ds_read_b64_tr_b16 v[154:155], v186 offset:16384
	ds_read_b64_tr_b16 v[156:157], v186 offset:18432
	s_waitcnt lgkmcnt(14)
	v_mfma_f32_32x32x16_bf16 v[18:33], v[86:89], v[158:161], v[18:33]
	ds_read_b64_tr_b16 v[158:159], v187 offset:16384
	ds_read_b64_tr_b16 v[160:161], v187 offset:18432
	s_waitcnt lgkmcnt(14)
	v_mfma_f32_32x32x16_bf16 v[34:49], v[86:89], v[162:165], v[34:49]
	ds_read_b64_tr_b16 v[162:163], v188 offset:16384
	ds_read_b64_tr_b16 v[164:165], v188 offset:18432
	s_waitcnt lgkmcnt(14)
	v_mfma_f32_32x32x16_bf16 v[50:65], v[86:89], v[166:169], v[50:65]
	ds_read_b64_tr_b16 v[166:167], v189 offset:16384
	ds_read_b64_tr_b16 v[168:169], v189 offset:18432
	s_waitcnt lgkmcnt(14)
	v_mfma_f32_32x32x16_bf16 v[2:17], v[82:85], v[170:173], v[2:17]
	ds_read_b64_tr_b16 v[170:171], v186 offset:20480
	ds_read_b64_tr_b16 v[172:173], v186 offset:22528
	s_waitcnt lgkmcnt(14)
	v_mfma_f32_32x32x16_bf16 v[18:33], v[82:85], v[174:177], v[18:33]
	ds_read_b64_tr_b16 v[174:175], v187 offset:20480
	ds_read_b64_tr_b16 v[176:177], v187 offset:22528
	s_waitcnt lgkmcnt(14)
	v_mfma_f32_32x32x16_bf16 v[34:49], v[82:85], v[178:181], v[34:49]
	ds_read_b64_tr_b16 v[178:179], v188 offset:20480
	ds_read_b64_tr_b16 v[180:181], v188 offset:22528
	s_waitcnt lgkmcnt(14)
	v_mfma_f32_32x32x16_bf16 v[50:65], v[82:85], v[182:185], v[50:65]
	ds_read_b64_tr_b16 v[182:183], v189 offset:20480
	ds_read_b64_tr_b16 v[184:185], v189 offset:22528
	s_waitcnt lgkmcnt(14)
	v_mfma_f32_32x32x16_bf16 v[2:17], v[78:81], v[154:157], v[2:17]
	ds_read_b64_tr_b16 v[154:155], v186 offset:24576
	ds_read_b64_tr_b16 v[156:157], v186 offset:26624
	s_waitcnt lgkmcnt(14)
	v_mfma_f32_32x32x16_bf16 v[18:33], v[78:81], v[158:161], v[18:33]
	ds_read_b64_tr_b16 v[158:159], v187 offset:24576
	ds_read_b64_tr_b16 v[160:161], v187 offset:26624
	s_waitcnt lgkmcnt(14)
	v_mfma_f32_32x32x16_bf16 v[34:49], v[78:81], v[162:165], v[34:49]
	ds_read_b64_tr_b16 v[162:163], v188 offset:24576
	ds_read_b64_tr_b16 v[164:165], v188 offset:26624
	s_waitcnt lgkmcnt(14)
	v_mfma_f32_32x32x16_bf16 v[50:65], v[78:81], v[166:169], v[50:65]
	ds_read_b64_tr_b16 v[166:167], v189 offset:24576
	ds_read_b64_tr_b16 v[168:169], v189 offset:26624
	s_waitcnt lgkmcnt(14)
	v_mfma_f32_32x32x16_bf16 v[2:17], v[74:77], v[170:173], v[2:17]
	s_waitcnt lgkmcnt(12)
	v_mfma_f32_32x32x16_bf16 v[18:33], v[74:77], v[174:177], v[18:33]
	s_waitcnt lgkmcnt(10)
	v_mfma_f32_32x32x16_bf16 v[34:49], v[74:77], v[178:181], v[34:49]
	s_waitcnt lgkmcnt(8)
	v_mfma_f32_32x32x16_bf16 v[50:65], v[74:77], v[182:185], v[50:65]
	s_waitcnt lgkmcnt(6)
	v_mfma_f32_32x32x16_bf16 v[2:17], v[70:73], v[154:157], v[2:17]
	s_waitcnt lgkmcnt(4)
	v_mfma_f32_32x32x16_bf16 v[18:33], v[70:73], v[158:161], v[18:33]
	s_waitcnt lgkmcnt(2)
	v_mfma_f32_32x32x16_bf16 v[34:49], v[70:73], v[162:165], v[34:49]
	s_waitcnt lgkmcnt(0)
	v_mfma_f32_32x32x16_bf16 v[50:65], v[70:73], v[166:169], v[50:65]
	v_add_u32_e32 v136, 0x17000, v136
	v_add_u32_e32 v135, v136, v135
	ds_read_b64_tr_b16 v[140:141], v135
	ds_read_b64_tr_b16 v[142:143], v135 offset:2048
	v_add_u32_e32 v135, v136, v137
	s_waitcnt lgkmcnt(0)
	v_mfma_f32_32x32x16_bf16 v[2:17], v[66:69], v[140:143], v[2:17]
	ds_read_b64_tr_b16 v[140:141], v135
	ds_read_b64_tr_b16 v[142:143], v135 offset:2048
	v_add_u32_e32 v135, v136, v138
	s_waitcnt lgkmcnt(0)
	v_mfma_f32_32x32x16_bf16 v[18:33], v[66:69], v[140:143], v[18:33]
	ds_read_b64_tr_b16 v[140:141], v135
	ds_read_b64_tr_b16 v[142:143], v135 offset:2048
	v_add_u32_e32 v135, v136, v139
	ds_read_b64_tr_b16 v[136:137], v135
	ds_read_b64_tr_b16 v[138:139], v135 offset:2048
	s_waitcnt lgkmcnt(2)
	v_mfma_f32_32x32x16_bf16 v[34:49], v[66:69], v[140:143], v[34:49]
	s_waitcnt lgkmcnt(0)
	v_mfma_f32_32x32x16_bf16 v[50:65], v[66:69], v[136:139], v[50:65]
	s_waitcnt vmcnt(4) lgkmcnt(0)
	s_barrier
	ds_read_b128 v[136:139], v130 offset:96
	ds_read_b128 v[140:143], v130 offset:64
	ds_read_b128 v[144:147], v130
	ds_read_b128 v[148:151], v130 offset:32
	s_waitcnt lgkmcnt(1)
	v_mul_f32_e32 v2, v2, v144
	v_lshl_add_u64 v[152:153], v[0:1], 1, s[28:29]
	v_cvt_pk_bf16_f32 v2, v2, s0
	global_store_short v[152:153], v2, off
	v_mul_f32_e32 v2, v18, v144
	v_cvt_pk_bf16_f32 v2, v2, s0
	global_store_short v[152:153], v2, off offset:64
	v_mul_f32_e32 v2, v34, v144
	v_cvt_pk_bf16_f32 v2, v2, s0
	global_store_short v[152:153], v2, off offset:128
	v_mul_f32_e32 v2, v50, v144
	v_cvt_pk_bf16_f32 v2, v2, s0
	global_store_short v[152:153], v2, off offset:192
	v_mul_f32_e32 v2, v3, v145
	v_cvt_pk_bf16_f32 v2, v2, s0
	global_store_short v[152:153], v2, off offset:2048
	v_mul_f32_e32 v2, v19, v145
	v_cvt_pk_bf16_f32 v2, v2, s0
	global_store_short v[152:153], v2, off offset:2112
	v_mul_f32_e32 v2, v35, v145
	v_cvt_pk_bf16_f32 v2, v2, s0
	global_store_short v[152:153], v2, off offset:2176
	v_mul_f32_e32 v2, v51, v145
	v_cvt_pk_bf16_f32 v2, v2, s0
	global_store_short v[152:153], v2, off offset:2240
	v_mul_f32_e32 v2, v4, v146
	v_cvt_pk_bf16_f32 v4, v2, s0
	v_add_co_u32_e32 v2, vcc, s21, v152
	s_nop 1
	v_addc_co_u32_e32 v3, vcc, 0, v153, vcc
	global_store_short v[2:3], v4, off
	v_mul_f32_e32 v4, v20, v146
	v_cvt_pk_bf16_f32 v4, v4, s0
	global_store_short v[2:3], v4, off offset:64
	v_mul_f32_e32 v4, v36, v146
	v_cvt_pk_bf16_f32 v4, v4, s0
	global_store_short v[2:3], v4, off offset:128
	v_mul_f32_e32 v4, v52, v146
	v_cvt_pk_bf16_f32 v4, v4, s0
	global_store_short v[2:3], v4, off offset:192
	v_mul_f32_e32 v4, v5, v147
	v_cvt_pk_bf16_f32 v4, v4, s0
	global_store_short v[2:3], v4, off offset:2048
	v_mul_f32_e32 v4, v21, v147
	v_cvt_pk_bf16_f32 v4, v4, s0
	global_store_short v[2:3], v4, off offset:2112
	v_mul_f32_e32 v4, v37, v147
	v_cvt_pk_bf16_f32 v4, v4, s0
	global_store_short v[2:3], v4, off offset:2176
	v_mul_f32_e32 v4, v53, v147
	v_cvt_pk_bf16_f32 v4, v4, s0
	global_store_short v[2:3], v4, off offset:2240
	s_waitcnt lgkmcnt(0)
	v_mul_f32_e32 v2, v6, v148
	v_cvt_pk_bf16_f32 v6, v2, s0
	v_add_co_u32_e32 v2, vcc, s14, v152
	s_nop 1
	v_addc_co_u32_e32 v3, vcc, 0, v153, vcc
	v_add_co_u32_e32 v4, vcc, s35, v152
	s_nop 1
	v_addc_co_u32_e32 v5, vcc, 0, v153, vcc
	global_store_short v[4:5], v6, off offset:-4096
	v_mul_f32_e32 v6, v22, v148
	v_cvt_pk_bf16_f32 v6, v6, s0
	global_store_short v[2:3], v6, off offset:64
	v_mul_f32_e32 v6, v38, v148
	v_cvt_pk_bf16_f32 v6, v6, s0
	global_store_short v[2:3], v6, off offset:128
	v_mul_f32_e32 v6, v54, v148
	v_cvt_pk_bf16_f32 v6, v6, s0
	global_store_short v[2:3], v6, off offset:192
	v_mul_f32_e32 v6, v7, v149
	v_cvt_pk_bf16_f32 v6, v6, s0
	global_store_short v[2:3], v6, off offset:2048
	v_mul_f32_e32 v6, v23, v149
	v_cvt_pk_bf16_f32 v6, v6, s0
	global_store_short v[2:3], v6, off offset:2112
	v_mul_f32_e32 v6, v39, v149
	v_cvt_pk_bf16_f32 v6, v6, s0
	global_store_short v[2:3], v6, off offset:2176
	v_mul_f32_e32 v6, v55, v149
	v_cvt_pk_bf16_f32 v6, v6, s0
	global_store_short v[2:3], v6, off offset:2240
	v_mul_f32_e32 v2, v8, v150
	v_cvt_pk_bf16_f32 v2, v2, s0
	global_store_short v[4:5], v2, off
	v_mul_f32_e32 v2, v24, v150
	v_cvt_pk_bf16_f32 v2, v2, s0
	global_store_short v[4:5], v2, off offset:64
	v_mul_f32_e32 v2, v40, v150
	v_cvt_pk_bf16_f32 v2, v2, s0
	global_store_short v[4:5], v2, off offset:128
	v_mul_f32_e32 v2, v56, v150
	v_cvt_pk_bf16_f32 v2, v2, s0
	global_store_short v[4:5], v2, off offset:192
	v_mul_f32_e32 v2, v9, v151
	v_cvt_pk_bf16_f32 v2, v2, s0
	global_store_short v[4:5], v2, off offset:2048
	v_mul_f32_e32 v2, v25, v151
	v_cvt_pk_bf16_f32 v2, v2, s0
	global_store_short v[4:5], v2, off offset:2112
	v_mul_f32_e32 v2, v41, v151
	v_cvt_pk_bf16_f32 v2, v2, s0
	global_store_short v[4:5], v2, off offset:2176
	v_mul_f32_e32 v2, v57, v151
	v_cvt_pk_bf16_f32 v2, v2, s0
	global_store_short v[4:5], v2, off offset:2240
	v_mul_f32_e32 v2, v10, v140
	v_cvt_pk_bf16_f32 v6, v2, s0
	v_add_co_u32_e32 v2, vcc, s81, v152
	s_nop 1
	v_addc_co_u32_e32 v3, vcc, 0, v153, vcc
	v_add_co_u32_e32 v4, vcc, s8, v152
	s_nop 1
	v_addc_co_u32_e32 v5, vcc, 0, v153, vcc
	global_store_short v[4:5], v6, off offset:-4096
	v_mul_f32_e32 v6, v26, v140
	v_cvt_pk_bf16_f32 v6, v6, s0
	global_store_short v[2:3], v6, off offset:64
	v_mul_f32_e32 v6, v42, v140
	v_cvt_pk_bf16_f32 v6, v6, s0
	global_store_short v[2:3], v6, off offset:128
	v_mul_f32_e32 v6, v58, v140
	v_cvt_pk_bf16_f32 v6, v6, s0
	global_store_short v[2:3], v6, off offset:192
	v_mul_f32_e32 v6, v11, v141
	v_cvt_pk_bf16_f32 v6, v6, s0
	global_store_short v[2:3], v6, off offset:2048
	v_mul_f32_e32 v6, v27, v141
	v_cvt_pk_bf16_f32 v6, v6, s0
	global_store_short v[2:3], v6, off offset:2112
	v_mul_f32_e32 v6, v43, v141
	v_cvt_pk_bf16_f32 v6, v6, s0
	global_store_short v[2:3], v6, off offset:2176
	v_mul_f32_e32 v6, v59, v141
	v_cvt_pk_bf16_f32 v6, v6, s0
	global_store_short v[2:3], v6, off offset:2240
	v_mul_f32_e32 v2, v12, v142
	v_cvt_pk_bf16_f32 v2, v2, s0
	global_store_short v[4:5], v2, off
	v_mul_f32_e32 v2, v28, v142
	v_cvt_pk_bf16_f32 v2, v2, s0
	global_store_short v[4:5], v2, off offset:64
	v_mul_f32_e32 v2, v44, v142
	v_cvt_pk_bf16_f32 v2, v2, s0
	global_store_short v[4:5], v2, off offset:128
	v_mul_f32_e32 v2, v60, v142
	v_cvt_pk_bf16_f32 v2, v2, s0
	global_store_short v[4:5], v2, off offset:192
	v_mul_f32_e32 v2, v13, v143
	v_cvt_pk_bf16_f32 v2, v2, s0
	global_store_short v[4:5], v2, off offset:2048
	v_mul_f32_e32 v2, v29, v143
	v_cvt_pk_bf16_f32 v2, v2, s0
	global_store_short v[4:5], v2, off offset:2112
	v_mul_f32_e32 v2, v45, v143
	v_cvt_pk_bf16_f32 v2, v2, s0
	global_store_short v[4:5], v2, off offset:2176
	v_mul_f32_e32 v2, v61, v143
	v_cvt_pk_bf16_f32 v2, v2, s0
	global_store_short v[4:5], v2, off offset:2240
	v_mul_f32_e32 v2, v14, v136
	v_cvt_pk_bf16_f32 v6, v2, s0
	v_add_co_u32_e32 v2, vcc, s18, v152
	s_nop 1
	v_addc_co_u32_e32 v3, vcc, 0, v153, vcc
	v_add_co_u32_e32 v4, vcc, s15, v152
	s_nop 1
	v_addc_co_u32_e32 v5, vcc, 0, v153, vcc
	global_store_short v[4:5], v6, off offset:-4096
	v_mul_f32_e32 v6, v30, v136
	v_cvt_pk_bf16_f32 v6, v6, s0
	global_store_short v[2:3], v6, off offset:64
	v_mul_f32_e32 v6, v46, v136
	v_cvt_pk_bf16_f32 v6, v6, s0
	global_store_short v[2:3], v6, off offset:128
	v_mul_f32_e32 v6, v62, v136
	v_cvt_pk_bf16_f32 v6, v6, s0
	global_store_short v[2:3], v6, off offset:192
	v_mul_f32_e32 v6, v15, v137
	v_cvt_pk_bf16_f32 v6, v6, s0
	global_store_short v[2:3], v6, off offset:2048
	v_mul_f32_e32 v6, v31, v137
	v_cvt_pk_bf16_f32 v6, v6, s0
	global_store_short v[2:3], v6, off offset:2112
	v_mul_f32_e32 v6, v47, v137
	v_cvt_pk_bf16_f32 v6, v6, s0
	global_store_short v[2:3], v6, off offset:2176
	v_mul_f32_e32 v6, v63, v137
	v_cvt_pk_bf16_f32 v6, v6, s0
	global_store_short v[2:3], v6, off offset:2240
	v_mul_f32_e32 v2, v16, v138
	v_cvt_pk_bf16_f32 v2, v2, s0
	global_store_short v[4:5], v2, off
	v_mul_f32_e32 v2, v32, v138
	v_cvt_pk_bf16_f32 v2, v2, s0
	global_store_short v[4:5], v2, off offset:64
	v_mul_f32_e32 v2, v48, v138
	v_cvt_pk_bf16_f32 v2, v2, s0
	global_store_short v[4:5], v2, off offset:128
	v_mul_f32_e32 v2, v64, v138
	v_cvt_pk_bf16_f32 v2, v2, s0
	global_store_short v[4:5], v2, off offset:192
	v_mul_f32_e32 v2, v17, v139
	v_cvt_pk_bf16_f32 v2, v2, s0
	global_store_short v[4:5], v2, off offset:2048
	v_mul_f32_e32 v2, v33, v139
	v_cvt_pk_bf16_f32 v2, v2, s0
	global_store_short v[4:5], v2, off offset:2112
	v_mul_f32_e32 v2, v49, v139
	v_cvt_pk_bf16_f32 v2, v2, s0
	global_store_short v[4:5], v2, off offset:2176
	v_mul_f32_e32 v2, v65, v139
	v_cvt_pk_bf16_f32 v2, v2, s0
	global_store_short v[4:5], v2, off offset:2240
	ds_read_b64_tr_b16 v[154:155], v131 offset:0
	ds_read_b64_tr_b16 v[156:157], v131 offset:2048
	ds_read_b64_tr_b16 v[158:159], v132 offset:0
	ds_read_b64_tr_b16 v[160:161], v132 offset:2048
	ds_read_b64_tr_b16 v[162:163], v133 offset:0
	ds_read_b64_tr_b16 v[164:165], v133 offset:2048
	ds_read_b64_tr_b16 v[166:167], v134 offset:0
	ds_read_b64_tr_b16 v[168:169], v134 offset:2048
	ds_read_b64_tr_b16 v[170:171], v131 offset:4096
	ds_read_b64_tr_b16 v[172:173], v131 offset:6144
	ds_read_b64_tr_b16 v[174:175], v132 offset:4096
	ds_read_b64_tr_b16 v[176:177], v132 offset:6144
	ds_read_b64_tr_b16 v[178:179], v133 offset:4096
	ds_read_b64_tr_b16 v[180:181], v133 offset:6144
	ds_read_b64_tr_b16 v[182:183], v134 offset:4096
	ds_read_b64_tr_b16 v[184:185], v134 offset:6144
	s_waitcnt lgkmcnt(14)
	v_mfma_f32_32x32x16_bf16 v[2:17], v[126:129], v[154:157], 0
	ds_read_b64_tr_b16 v[154:155], v131 offset:8192
	ds_read_b64_tr_b16 v[156:157], v131 offset:10240
	s_waitcnt lgkmcnt(14)
	v_mfma_f32_32x32x16_bf16 v[18:33], v[126:129], v[158:161], 0
	ds_read_b64_tr_b16 v[158:159], v132 offset:8192
	ds_read_b64_tr_b16 v[160:161], v132 offset:10240
	s_waitcnt lgkmcnt(14)
	v_mfma_f32_32x32x16_bf16 v[34:49], v[126:129], v[162:165], 0
	ds_read_b64_tr_b16 v[162:163], v133 offset:8192
	ds_read_b64_tr_b16 v[164:165], v133 offset:10240
	s_waitcnt lgkmcnt(14)
	v_mfma_f32_32x32x16_bf16 v[50:65], v[126:129], v[166:169], 0
	ds_read_b64_tr_b16 v[166:167], v134 offset:8192
	ds_read_b64_tr_b16 v[168:169], v134 offset:10240
	s_waitcnt lgkmcnt(14)
	v_mfma_f32_32x32x16_bf16 v[2:17], v[122:125], v[170:173], v[2:17]
	ds_read_b64_tr_b16 v[170:171], v131 offset:12288
	ds_read_b64_tr_b16 v[172:173], v131 offset:14336
	s_waitcnt lgkmcnt(14)
	v_mfma_f32_32x32x16_bf16 v[18:33], v[122:125], v[174:177], v[18:33]
	ds_read_b64_tr_b16 v[174:175], v132 offset:12288
	ds_read_b64_tr_b16 v[176:177], v132 offset:14336
	s_waitcnt lgkmcnt(14)
	v_mfma_f32_32x32x16_bf16 v[34:49], v[122:125], v[178:181], v[34:49]
	ds_read_b64_tr_b16 v[178:179], v133 offset:12288
	ds_read_b64_tr_b16 v[180:181], v133 offset:14336
	s_waitcnt lgkmcnt(14)
	v_mfma_f32_32x32x16_bf16 v[50:65], v[122:125], v[182:185], v[50:65]
	ds_read_b64_tr_b16 v[182:183], v134 offset:12288
	ds_read_b64_tr_b16 v[184:185], v134 offset:14336
	s_waitcnt lgkmcnt(14)
	v_mfma_f32_32x32x16_bf16 v[2:17], v[118:121], v[154:157], v[2:17]
	ds_read_b64_tr_b16 v[154:155], v131 offset:16384
	ds_read_b64_tr_b16 v[156:157], v131 offset:18432
	s_waitcnt lgkmcnt(14)
	v_mfma_f32_32x32x16_bf16 v[18:33], v[118:121], v[158:161], v[18:33]
	ds_read_b64_tr_b16 v[158:159], v132 offset:16384
	ds_read_b64_tr_b16 v[160:161], v132 offset:18432
	s_waitcnt lgkmcnt(14)
	v_mfma_f32_32x32x16_bf16 v[34:49], v[118:121], v[162:165], v[34:49]
	ds_read_b64_tr_b16 v[162:163], v133 offset:16384
	ds_read_b64_tr_b16 v[164:165], v133 offset:18432
	s_waitcnt lgkmcnt(14)
	v_mfma_f32_32x32x16_bf16 v[50:65], v[118:121], v[166:169], v[50:65]
	ds_read_b64_tr_b16 v[166:167], v134 offset:16384
	ds_read_b64_tr_b16 v[168:169], v134 offset:18432
	s_waitcnt lgkmcnt(14)
	v_mfma_f32_32x32x16_bf16 v[2:17], v[114:117], v[170:173], v[2:17]
	ds_read_b64_tr_b16 v[170:171], v131 offset:20480
	ds_read_b64_tr_b16 v[172:173], v131 offset:22528
	s_waitcnt lgkmcnt(14)
	v_mfma_f32_32x32x16_bf16 v[18:33], v[114:117], v[174:177], v[18:33]
	ds_read_b64_tr_b16 v[174:175], v132 offset:20480
	ds_read_b64_tr_b16 v[176:177], v132 offset:22528
	s_waitcnt lgkmcnt(14)
	v_mfma_f32_32x32x16_bf16 v[34:49], v[114:117], v[178:181], v[34:49]
	ds_read_b64_tr_b16 v[178:179], v133 offset:20480
	ds_read_b64_tr_b16 v[180:181], v133 offset:22528
	s_waitcnt lgkmcnt(14)
	v_mfma_f32_32x32x16_bf16 v[50:65], v[114:117], v[182:185], v[50:65]
	ds_read_b64_tr_b16 v[182:183], v134 offset:20480
	ds_read_b64_tr_b16 v[184:185], v134 offset:22528
	s_waitcnt lgkmcnt(14)
	v_mfma_f32_32x32x16_bf16 v[2:17], v[110:113], v[154:157], v[2:17]
	ds_read_b64_tr_b16 v[154:155], v131 offset:24576
	ds_read_b64_tr_b16 v[156:157], v131 offset:26624
	s_waitcnt lgkmcnt(14)
	v_mfma_f32_32x32x16_bf16 v[18:33], v[110:113], v[158:161], v[18:33]
	ds_read_b64_tr_b16 v[158:159], v132 offset:24576
	ds_read_b64_tr_b16 v[160:161], v132 offset:26624
	s_waitcnt lgkmcnt(14)
	v_mfma_f32_32x32x16_bf16 v[34:49], v[110:113], v[162:165], v[34:49]
	ds_read_b64_tr_b16 v[162:163], v133 offset:24576
	ds_read_b64_tr_b16 v[164:165], v133 offset:26624
	s_waitcnt lgkmcnt(14)
	v_mfma_f32_32x32x16_bf16 v[50:65], v[110:113], v[166:169], v[50:65]
	ds_read_b64_tr_b16 v[166:167], v134 offset:24576
	ds_read_b64_tr_b16 v[168:169], v134 offset:26624
	s_waitcnt lgkmcnt(14)
	v_mfma_f32_32x32x16_bf16 v[2:17], v[106:109], v[170:173], v[2:17]
	ds_read_b64_tr_b16 v[170:171], v131 offset:28672
	ds_read_b64_tr_b16 v[172:173], v131 offset:30720
	s_waitcnt lgkmcnt(14)
	v_mfma_f32_32x32x16_bf16 v[18:33], v[106:109], v[174:177], v[18:33]
	ds_read_b64_tr_b16 v[174:175], v132 offset:28672
	ds_read_b64_tr_b16 v[176:177], v132 offset:30720
	s_waitcnt lgkmcnt(14)
	v_mfma_f32_32x32x16_bf16 v[34:49], v[106:109], v[178:181], v[34:49]
	ds_read_b64_tr_b16 v[178:179], v133 offset:28672
	ds_read_b64_tr_b16 v[180:181], v133 offset:30720
	s_waitcnt lgkmcnt(14)
	v_mfma_f32_32x32x16_bf16 v[50:65], v[106:109], v[182:185], v[50:65]
	ds_read_b64_tr_b16 v[182:183], v134 offset:28672
	ds_read_b64_tr_b16 v[184:185], v134 offset:30720
	s_waitcnt lgkmcnt(14)
	v_mfma_f32_32x32x16_bf16 v[2:17], v[102:105], v[154:157], v[2:17]
	s_waitcnt lgkmcnt(12)
	v_mfma_f32_32x32x16_bf16 v[18:33], v[102:105], v[158:161], v[18:33]
	s_waitcnt lgkmcnt(10)
	v_mfma_f32_32x32x16_bf16 v[34:49], v[102:105], v[162:165], v[34:49]
	s_waitcnt lgkmcnt(8)
	v_mfma_f32_32x32x16_bf16 v[50:65], v[102:105], v[166:169], v[50:65]
	s_waitcnt lgkmcnt(6)
	v_mfma_f32_32x32x16_bf16 v[2:17], v[98:101], v[170:173], v[2:17]
	s_waitcnt lgkmcnt(4)
	v_mfma_f32_32x32x16_bf16 v[18:33], v[98:101], v[174:177], v[18:33]
	s_waitcnt lgkmcnt(2)
	v_mfma_f32_32x32x16_bf16 v[34:49], v[98:101], v[178:181], v[34:49]
	s_waitcnt lgkmcnt(0)
	v_mfma_f32_32x32x16_bf16 v[50:65], v[98:101], v[182:185], v[50:65]
	s_waitcnt vmcnt(0) lgkmcnt(0)
	s_barrier
	ds_read_b64_tr_b16 v[154:155], v131 offset:32768
	ds_read_b64_tr_b16 v[156:157], v131 offset:34816
	ds_read_b64_tr_b16 v[158:159], v132 offset:32768
	ds_read_b64_tr_b16 v[160:161], v132 offset:34816
	ds_read_b64_tr_b16 v[162:163], v133 offset:32768
	ds_read_b64_tr_b16 v[164:165], v133 offset:34816
	ds_read_b64_tr_b16 v[166:167], v134 offset:32768
	ds_read_b64_tr_b16 v[168:169], v134 offset:34816
	ds_read_b64_tr_b16 v[170:171], v131 offset:36864
	ds_read_b64_tr_b16 v[172:173], v131 offset:38912
	ds_read_b64_tr_b16 v[174:175], v132 offset:36864
	ds_read_b64_tr_b16 v[176:177], v132 offset:38912
	ds_read_b64_tr_b16 v[178:179], v133 offset:36864
	ds_read_b64_tr_b16 v[180:181], v133 offset:38912
	ds_read_b64_tr_b16 v[182:183], v134 offset:36864
	ds_read_b64_tr_b16 v[184:185], v134 offset:38912
	s_waitcnt lgkmcnt(14)
	v_mfma_f32_32x32x16_bf16 v[2:17], v[94:97], v[154:157], v[2:17]
	ds_read_b64_tr_b16 v[154:155], v131 offset:40960
	ds_read_b64_tr_b16 v[156:157], v131 offset:43008
	s_waitcnt lgkmcnt(14)
	v_mfma_f32_32x32x16_bf16 v[18:33], v[94:97], v[158:161], v[18:33]
	ds_read_b64_tr_b16 v[158:159], v132 offset:40960
	ds_read_b64_tr_b16 v[160:161], v132 offset:43008
	s_waitcnt lgkmcnt(14)
	v_mfma_f32_32x32x16_bf16 v[34:49], v[94:97], v[162:165], v[34:49]
	ds_read_b64_tr_b16 v[162:163], v133 offset:40960
	ds_read_b64_tr_b16 v[164:165], v133 offset:43008
	s_waitcnt lgkmcnt(14)
	v_mfma_f32_32x32x16_bf16 v[50:65], v[94:97], v[166:169], v[50:65]
	ds_read_b64_tr_b16 v[166:167], v134 offset:40960
	ds_read_b64_tr_b16 v[168:169], v134 offset:43008
	s_waitcnt lgkmcnt(14)
	v_mfma_f32_32x32x16_bf16 v[2:17], v[90:93], v[170:173], v[2:17]
	ds_read_b64_tr_b16 v[170:171], v131 offset:45056
	ds_read_b64_tr_b16 v[172:173], v131 offset:47104
	s_waitcnt lgkmcnt(14)
	v_mfma_f32_32x32x16_bf16 v[18:33], v[90:93], v[174:177], v[18:33]
	ds_read_b64_tr_b16 v[174:175], v132 offset:45056
	ds_read_b64_tr_b16 v[176:177], v132 offset:47104
	s_waitcnt lgkmcnt(14)
	v_mfma_f32_32x32x16_bf16 v[34:49], v[90:93], v[178:181], v[34:49]
	ds_read_b64_tr_b16 v[178:179], v133 offset:45056
	ds_read_b64_tr_b16 v[180:181], v133 offset:47104
	s_waitcnt lgkmcnt(14)
	v_mfma_f32_32x32x16_bf16 v[50:65], v[90:93], v[182:185], v[50:65]
	ds_read_b64_tr_b16 v[182:183], v134 offset:45056
	ds_read_b64_tr_b16 v[184:185], v134 offset:47104
	s_waitcnt lgkmcnt(14)
	v_mfma_f32_32x32x16_bf16 v[2:17], v[86:89], v[154:157], v[2:17]
	ds_read_b64_tr_b16 v[154:155], v131 offset:49152
	ds_read_b64_tr_b16 v[156:157], v131 offset:51200
	s_waitcnt lgkmcnt(14)
	v_mfma_f32_32x32x16_bf16 v[18:33], v[86:89], v[158:161], v[18:33]
	ds_read_b64_tr_b16 v[158:159], v132 offset:49152
	ds_read_b64_tr_b16 v[160:161], v132 offset:51200
	s_waitcnt lgkmcnt(14)
	v_mfma_f32_32x32x16_bf16 v[34:49], v[86:89], v[162:165], v[34:49]
	ds_read_b64_tr_b16 v[162:163], v133 offset:49152
	ds_read_b64_tr_b16 v[164:165], v133 offset:51200
	s_waitcnt lgkmcnt(14)
	v_mfma_f32_32x32x16_bf16 v[50:65], v[86:89], v[166:169], v[50:65]
	ds_read_b64_tr_b16 v[166:167], v134 offset:49152
	ds_read_b64_tr_b16 v[168:169], v134 offset:51200
	s_waitcnt lgkmcnt(14)
	v_mfma_f32_32x32x16_bf16 v[2:17], v[82:85], v[170:173], v[2:17]
	ds_read_b64_tr_b16 v[170:171], v131 offset:53248
	ds_read_b64_tr_b16 v[172:173], v131 offset:55296
	s_waitcnt lgkmcnt(14)
	v_mfma_f32_32x32x16_bf16 v[18:33], v[82:85], v[174:177], v[18:33]
	ds_read_b64_tr_b16 v[174:175], v132 offset:53248
	ds_read_b64_tr_b16 v[176:177], v132 offset:55296
	s_waitcnt lgkmcnt(14)
	v_mfma_f32_32x32x16_bf16 v[34:49], v[82:85], v[178:181], v[34:49]
	ds_read_b64_tr_b16 v[178:179], v133 offset:53248
	ds_read_b64_tr_b16 v[180:181], v133 offset:55296
	s_waitcnt lgkmcnt(14)
	v_mfma_f32_32x32x16_bf16 v[50:65], v[82:85], v[182:185], v[50:65]
	ds_read_b64_tr_b16 v[182:183], v134 offset:53248
	ds_read_b64_tr_b16 v[184:185], v134 offset:55296
	s_waitcnt lgkmcnt(14)
	v_mfma_f32_32x32x16_bf16 v[2:17], v[78:81], v[154:157], v[2:17]
	ds_read_b64_tr_b16 v[154:155], v131 offset:57344
	ds_read_b64_tr_b16 v[156:157], v131 offset:59392
	s_waitcnt lgkmcnt(14)
	v_mfma_f32_32x32x16_bf16 v[18:33], v[78:81], v[158:161], v[18:33]
	ds_read_b64_tr_b16 v[158:159], v132 offset:57344
	ds_read_b64_tr_b16 v[160:161], v132 offset:59392
	s_waitcnt lgkmcnt(14)
	v_mfma_f32_32x32x16_bf16 v[34:49], v[78:81], v[162:165], v[34:49]
	ds_read_b64_tr_b16 v[162:163], v133 offset:57344
	ds_read_b64_tr_b16 v[164:165], v133 offset:59392
	s_waitcnt lgkmcnt(14)
	v_mfma_f32_32x32x16_bf16 v[50:65], v[78:81], v[166:169], v[50:65]
	ds_read_b64_tr_b16 v[166:167], v134 offset:57344
	ds_read_b64_tr_b16 v[168:169], v134 offset:59392
	s_waitcnt lgkmcnt(14)
	v_mfma_f32_32x32x16_bf16 v[2:17], v[74:77], v[170:173], v[2:17]
	ds_read_b64_tr_b16 v[170:171], v131 offset:61440
	ds_read_b64_tr_b16 v[172:173], v131 offset:63488
	s_waitcnt lgkmcnt(14)
	v_mfma_f32_32x32x16_bf16 v[18:33], v[74:77], v[174:177], v[18:33]
	ds_read_b64_tr_b16 v[174:175], v132 offset:61440
	ds_read_b64_tr_b16 v[176:177], v132 offset:63488
	s_waitcnt lgkmcnt(14)
	v_mfma_f32_32x32x16_bf16 v[34:49], v[74:77], v[178:181], v[34:49]
	ds_read_b64_tr_b16 v[178:179], v133 offset:61440
	ds_read_b64_tr_b16 v[180:181], v133 offset:63488
	s_waitcnt lgkmcnt(14)
	v_mfma_f32_32x32x16_bf16 v[50:65], v[74:77], v[182:185], v[50:65]
	ds_read_b64_tr_b16 v[182:183], v134 offset:61440
	ds_read_b64_tr_b16 v[184:185], v134 offset:63488
	s_waitcnt lgkmcnt(14)
	v_mfma_f32_32x32x16_bf16 v[2:17], v[70:73], v[154:157], v[2:17]
	s_waitcnt lgkmcnt(12)
	v_mfma_f32_32x32x16_bf16 v[18:33], v[70:73], v[158:161], v[18:33]
	s_waitcnt lgkmcnt(10)
	v_mfma_f32_32x32x16_bf16 v[34:49], v[70:73], v[162:165], v[34:49]
	s_waitcnt lgkmcnt(8)
	v_mfma_f32_32x32x16_bf16 v[50:65], v[70:73], v[166:169], v[50:65]
	s_waitcnt lgkmcnt(6)
	v_mfma_f32_32x32x16_bf16 v[2:17], v[66:69], v[170:173], v[2:17]
	s_waitcnt lgkmcnt(4)
	v_mfma_f32_32x32x16_bf16 v[18:33], v[66:69], v[174:177], v[18:33]
	s_waitcnt lgkmcnt(2)
	v_mfma_f32_32x32x16_bf16 v[34:49], v[66:69], v[178:181], v[34:49]
	s_waitcnt lgkmcnt(0)
	v_mfma_f32_32x32x16_bf16 v[50:65], v[66:69], v[182:185], v[50:65]
	s_waitcnt vmcnt(0) lgkmcnt(0)
	s_barrier
	ds_read_b128 v[66:69], v130
	ds_read_b128 v[70:73], v130 offset:96
	ds_read_b128 v[74:77], v130 offset:64
	ds_read_b128 v[78:81], v130 offset:32
	s_add_u32 s30, s30, s90
	v_lshl_add_u64 v[82:83], v[0:1], 1, s[28:29]
	s_waitcnt lgkmcnt(3)
	v_mul_f32_e32 v0, v2, v66
	v_cvt_pk_bf16_f32 v0, v0, s0
	global_store_short v[82:83], v0, off offset:256
	v_mul_f32_e32 v0, v18, v66
	v_cvt_pk_bf16_f32 v0, v0, s0
	global_store_short v[82:83], v0, off offset:320
	v_mul_f32_e32 v0, v34, v66
	v_cvt_pk_bf16_f32 v0, v0, s0
	global_store_short v[82:83], v0, off offset:384
	v_mul_f32_e32 v0, v50, v66
	v_cvt_pk_bf16_f32 v0, v0, s0
	global_store_short v[82:83], v0, off offset:448
	v_mul_f32_e32 v0, v3, v67
	v_cvt_pk_bf16_f32 v0, v0, s0
	global_store_short v[82:83], v0, off offset:2304
	v_mul_f32_e32 v0, v19, v67
	v_cvt_pk_bf16_f32 v0, v0, s0
	global_store_short v[82:83], v0, off offset:2368
	v_mul_f32_e32 v0, v35, v67
	v_cvt_pk_bf16_f32 v0, v0, s0
	global_store_short v[82:83], v0, off offset:2432
	v_mul_f32_e32 v0, v51, v67
	v_cvt_pk_bf16_f32 v0, v0, s0
	global_store_short v[82:83], v0, off offset:2496
	v_mul_f32_e32 v0, v4, v68
	v_add_co_u32_e32 v2, vcc, s21, v82
	v_cvt_pk_bf16_f32 v0, v0, s0
	s_nop 0
	v_addc_co_u32_e32 v3, vcc, 0, v83, vcc
	global_store_short v[2:3], v0, off offset:256
	v_mul_f32_e32 v0, v20, v68
	v_cvt_pk_bf16_f32 v0, v0, s0
	global_store_short v[2:3], v0, off offset:320
	v_mul_f32_e32 v0, v36, v68
	v_cvt_pk_bf16_f32 v0, v0, s0
	global_store_short v[2:3], v0, off offset:384
	v_mul_f32_e32 v0, v52, v68
	v_cvt_pk_bf16_f32 v0, v0, s0
	global_store_short v[2:3], v0, off offset:448
	v_mul_f32_e32 v0, v5, v69
	v_cvt_pk_bf16_f32 v0, v0, s0
	global_store_short v[2:3], v0, off offset:2304
	v_mul_f32_e32 v0, v21, v69
	v_cvt_pk_bf16_f32 v0, v0, s0
	global_store_short v[2:3], v0, off offset:2368
	v_mul_f32_e32 v0, v37, v69
	v_cvt_pk_bf16_f32 v0, v0, s0
	global_store_short v[2:3], v0, off offset:2432
	v_mul_f32_e32 v0, v53, v69
	v_cvt_pk_bf16_f32 v0, v0, s0
	global_store_short v[2:3], v0, off offset:2496
	s_waitcnt lgkmcnt(0)
	v_mul_f32_e32 v0, v6, v78
	v_add_co_u32_e32 v2, vcc, s14, v82
	v_cvt_pk_bf16_f32 v0, v0, s0
	s_nop 0
	v_addc_co_u32_e32 v3, vcc, 0, v83, vcc
	global_store_short v[2:3], v0, off offset:256
	v_mul_f32_e32 v0, v22, v78
	v_cvt_pk_bf16_f32 v0, v0, s0
	global_store_short v[2:3], v0, off offset:320
	v_mul_f32_e32 v0, v38, v78
	v_cvt_pk_bf16_f32 v0, v0, s0
	global_store_short v[2:3], v0, off offset:384
	v_mul_f32_e32 v0, v54, v78
	v_cvt_pk_bf16_f32 v0, v0, s0
	global_store_short v[2:3], v0, off offset:448
	v_mul_f32_e32 v0, v7, v79
	v_cvt_pk_bf16_f32 v0, v0, s0
	global_store_short v[2:3], v0, off offset:2304
	v_mul_f32_e32 v0, v23, v79
	v_cvt_pk_bf16_f32 v0, v0, s0
	global_store_short v[2:3], v0, off offset:2368
	v_mul_f32_e32 v0, v39, v79
	v_cvt_pk_bf16_f32 v0, v0, s0
	global_store_short v[2:3], v0, off offset:2432
	v_mul_f32_e32 v0, v55, v79
	v_cvt_pk_bf16_f32 v0, v0, s0
	global_store_short v[2:3], v0, off offset:2496
	v_mul_f32_e32 v0, v8, v80
	v_add_co_u32_e32 v2, vcc, s35, v82
	v_cvt_pk_bf16_f32 v0, v0, s0
	s_nop 0
	v_addc_co_u32_e32 v3, vcc, 0, v83, vcc
	global_store_short v[2:3], v0, off offset:256
	v_mul_f32_e32 v0, v24, v80
	v_cvt_pk_bf16_f32 v0, v0, s0
	global_store_short v[2:3], v0, off offset:320
	v_mul_f32_e32 v0, v40, v80
	v_cvt_pk_bf16_f32 v0, v0, s0
	global_store_short v[2:3], v0, off offset:384
	v_mul_f32_e32 v0, v56, v80
	v_cvt_pk_bf16_f32 v0, v0, s0
	global_store_short v[2:3], v0, off offset:448
	v_mul_f32_e32 v0, v9, v81
	v_cvt_pk_bf16_f32 v0, v0, s0
	global_store_short v[2:3], v0, off offset:2304
	v_mul_f32_e32 v0, v25, v81
	v_cvt_pk_bf16_f32 v0, v0, s0
	global_store_short v[2:3], v0, off offset:2368
	v_mul_f32_e32 v0, v41, v81
	v_cvt_pk_bf16_f32 v0, v0, s0
	global_store_short v[2:3], v0, off offset:2432
	v_mul_f32_e32 v0, v57, v81
	v_cvt_pk_bf16_f32 v0, v0, s0
	global_store_short v[2:3], v0, off offset:2496
	v_mul_f32_e32 v0, v10, v74
	v_add_co_u32_e32 v2, vcc, s81, v82
	v_cvt_pk_bf16_f32 v0, v0, s0
	s_nop 0
	v_addc_co_u32_e32 v3, vcc, 0, v83, vcc
	global_store_short v[2:3], v0, off offset:256
	v_mul_f32_e32 v0, v26, v74
	v_cvt_pk_bf16_f32 v0, v0, s0
	global_store_short v[2:3], v0, off offset:320
	v_mul_f32_e32 v0, v42, v74
	v_cvt_pk_bf16_f32 v0, v0, s0
	global_store_short v[2:3], v0, off offset:384
	v_mul_f32_e32 v0, v58, v74
	v_cvt_pk_bf16_f32 v0, v0, s0
	global_store_short v[2:3], v0, off offset:448
	v_mul_f32_e32 v0, v11, v75
	v_cvt_pk_bf16_f32 v0, v0, s0
	global_store_short v[2:3], v0, off offset:2304
	v_mul_f32_e32 v0, v27, v75
	v_cvt_pk_bf16_f32 v0, v0, s0
	global_store_short v[2:3], v0, off offset:2368
	v_mul_f32_e32 v0, v43, v75
	v_cvt_pk_bf16_f32 v0, v0, s0
	global_store_short v[2:3], v0, off offset:2432
	v_mul_f32_e32 v0, v59, v75
	v_cvt_pk_bf16_f32 v0, v0, s0
	global_store_short v[2:3], v0, off offset:2496
	v_mul_f32_e32 v0, v12, v76
	v_add_co_u32_e32 v2, vcc, s8, v82
	v_cvt_pk_bf16_f32 v0, v0, s0
	s_nop 0
	v_addc_co_u32_e32 v3, vcc, 0, v83, vcc
	global_store_short v[2:3], v0, off offset:256
	v_mul_f32_e32 v0, v28, v76
	v_cvt_pk_bf16_f32 v0, v0, s0
	global_store_short v[2:3], v0, off offset:320
	v_mul_f32_e32 v0, v44, v76
	v_cvt_pk_bf16_f32 v0, v0, s0
	global_store_short v[2:3], v0, off offset:384
	v_mul_f32_e32 v0, v60, v76
	v_cvt_pk_bf16_f32 v0, v0, s0
	global_store_short v[2:3], v0, off offset:448
	v_mul_f32_e32 v0, v13, v77
	v_cvt_pk_bf16_f32 v0, v0, s0
	global_store_short v[2:3], v0, off offset:2304
	v_mul_f32_e32 v0, v29, v77
	v_cvt_pk_bf16_f32 v0, v0, s0
	global_store_short v[2:3], v0, off offset:2368
	v_mul_f32_e32 v0, v45, v77
	v_cvt_pk_bf16_f32 v0, v0, s0
	global_store_short v[2:3], v0, off offset:2432
	v_mul_f32_e32 v0, v61, v77
	v_cvt_pk_bf16_f32 v0, v0, s0
	global_store_short v[2:3], v0, off offset:2496
	v_mul_f32_e32 v0, v14, v70
	v_add_co_u32_e32 v2, vcc, s18, v82
	v_cvt_pk_bf16_f32 v0, v0, s0
	s_nop 0
	v_addc_co_u32_e32 v3, vcc, 0, v83, vcc
	global_store_short v[2:3], v0, off offset:256
	v_mul_f32_e32 v0, v30, v70
	v_cvt_pk_bf16_f32 v0, v0, s0
	global_store_short v[2:3], v0, off offset:320
	v_mul_f32_e32 v0, v46, v70
	v_cvt_pk_bf16_f32 v0, v0, s0
	global_store_short v[2:3], v0, off offset:384
	v_mul_f32_e32 v0, v62, v70
	v_cvt_pk_bf16_f32 v0, v0, s0
	global_store_short v[2:3], v0, off offset:448
	v_mul_f32_e32 v0, v15, v71
	v_cvt_pk_bf16_f32 v0, v0, s0
	global_store_short v[2:3], v0, off offset:2304
	v_mul_f32_e32 v0, v31, v71
	v_cvt_pk_bf16_f32 v0, v0, s0
	global_store_short v[2:3], v0, off offset:2368
	v_mul_f32_e32 v0, v47, v71
	v_cvt_pk_bf16_f32 v0, v0, s0
	global_store_short v[2:3], v0, off offset:2432
	v_mul_f32_e32 v0, v63, v71
	v_cvt_pk_bf16_f32 v0, v0, s0
	global_store_short v[2:3], v0, off offset:2496
	v_mul_f32_e32 v0, v16, v72
	v_add_co_u32_e32 v2, vcc, s15, v82
	v_cvt_pk_bf16_f32 v0, v0, s0
	s_nop 0
	v_addc_co_u32_e32 v3, vcc, 0, v83, vcc
	global_store_short v[2:3], v0, off offset:256
	v_mul_f32_e32 v0, v32, v72
	v_cvt_pk_bf16_f32 v0, v0, s0
	global_store_short v[2:3], v0, off offset:320
	v_mul_f32_e32 v0, v48, v72
	v_cvt_pk_bf16_f32 v0, v0, s0
	global_store_short v[2:3], v0, off offset:384
	v_mul_f32_e32 v0, v64, v72
	v_cvt_pk_bf16_f32 v0, v0, s0
	global_store_short v[2:3], v0, off offset:448
	v_mul_f32_e32 v0, v17, v73
	v_cvt_pk_bf16_f32 v0, v0, s0
	global_store_short v[2:3], v0, off offset:2304
	v_mul_f32_e32 v0, v33, v73
	v_cvt_pk_bf16_f32 v0, v0, s0
	global_store_short v[2:3], v0, off offset:2368
	v_mul_f32_e32 v0, v49, v73
	v_cvt_pk_bf16_f32 v0, v0, s0
	global_store_short v[2:3], v0, off offset:2432
	v_mul_f32_e32 v0, v65, v73
	v_readlane_b32 s9, v251, 36
	v_cvt_pk_bf16_f32 v0, v0, s0
	s_addc_u32 s31, s31, s9
	s_mov_b64 s[42:43], 0
	global_store_short v[2:3], v0, off offset:2496

.LBB0_494:
	s_lshl_b32 s9, s65, 8
	v_readlane_b32 s10, v251, 7
	s_add_i32 s42, s9, s10
	s_ashr_i32 s43, s42, 31
	s_lshl_b64 s[10:11], s[42:43], 11
	s_add_u32 s9, s16, s10
	s_addc_u32 s22, s17, s11
	s_lshl_b32 s44, s64, 8
	v_mov_b32_e32 v195, v226
	v_mov_b32_e32 v0, v227
	s_ashr_i32 s45, s44, 31
	s_lshl_b64 s[10:11], s[44:45], 1
	v_and_b32_e32 v203, 31, v195
	v_ashrrev_i32_e32 v202, 5, v195
	s_add_u32 s50, s9, s10
	v_lshlrev_b32_e32 v0, 10, v203
	s_addc_u32 s51, s22, s11
	v_lshl_add_u32 v0, v202, 3, v0
	v_lshl_add_u64 v[2:3], v[0:1], 1, s[50:51]
	global_load_dwordx4 v[2:5], v[2:3], off
	v_add_u32_e32 v6, 16, v0
	v_mov_b32_e32 v7, v1
	v_lshl_add_u64 v[6:7], v[6:7], 1, s[50:51]
	global_load_dwordx4 v[186:189], v[6:7], off
	v_add_u32_e32 v6, 32, v0
	v_mov_b32_e32 v7, v1
	v_lshl_add_u64 v[6:7], v[6:7], 1, s[50:51]
	global_load_dwordx4 v[182:185], v[6:7], off
	v_add_u32_e32 v6, 48, v0
	v_mov_b32_e32 v7, v1
	v_lshl_add_u64 v[6:7], v[6:7], 1, s[50:51]
	global_load_dwordx4 v[178:181], v[6:7], off
	v_add_u32_e32 v6, 64, v0
	v_mov_b32_e32 v7, v1
	v_lshl_add_u64 v[6:7], v[6:7], 1, s[50:51]
	global_load_dwordx4 v[174:177], v[6:7], off
	v_add_u32_e32 v6, 0x50, v0
	v_mov_b32_e32 v7, v1
	v_lshl_add_u64 v[6:7], v[6:7], 1, s[50:51]
	global_load_dwordx4 v[170:173], v[6:7], off
	v_add_u32_e32 v6, 0x60, v0
	v_mov_b32_e32 v7, v1
	v_lshl_add_u64 v[6:7], v[6:7], 1, s[50:51]
	global_load_dwordx4 v[166:169], v[6:7], off
	v_add_u32_e32 v6, 0x70, v0
	v_mov_b32_e32 v7, v1
	v_lshl_add_u64 v[6:7], v[6:7], 1, s[50:51]
	global_load_dwordx4 v[162:165], v[6:7], off
	v_add_u32_e32 v6, 0x80, v0
	v_mov_b32_e32 v7, v1
	v_lshl_add_u64 v[6:7], v[6:7], 1, s[50:51]
	global_load_dwordx4 v[158:161], v[6:7], off
	v_add_u32_e32 v6, 0x90, v0
	v_mov_b32_e32 v7, v1
	v_lshl_add_u64 v[6:7], v[6:7], 1, s[50:51]
	global_load_dwordx4 v[154:157], v[6:7], off
	v_add_u32_e32 v6, 0xa0, v0
	v_mov_b32_e32 v7, v1
	v_lshl_add_u64 v[6:7], v[6:7], 1, s[50:51]
	global_load_dwordx4 v[150:153], v[6:7], off
	v_add_u32_e32 v6, 0xb0, v0
	v_mov_b32_e32 v7, v1
	v_lshl_add_u64 v[6:7], v[6:7], 1, s[50:51]
	s_lshl_b32 s9, s65, 4
	global_load_dwordx4 v[146:149], v[6:7], off
	v_add_u32_e32 v6, 0xc0, v0
	v_mov_b32_e32 v7, v1
	s_and_b32 s22, s9, 0xffffff00
	v_lshl_add_u64 v[6:7], v[6:7], 1, s[50:51]
	s_ashr_i32 s23, s22, 31
	global_load_dwordx4 v[142:145], v[6:7], off
	v_add_u32_e32 v6, 0xd0, v0
	v_mov_b32_e32 v7, v1
	s_lshl_b64 s[22:23], s[22:23], 12
	v_lshl_add_u64 v[6:7], v[6:7], 1, s[50:51]
	s_add_u32 s9, s1, s22
	global_load_dwordx4 v[138:141], v[6:7], off
	v_add_u32_e32 v6, 0xe0, v0
	v_mov_b32_e32 v7, v1
	s_addc_u32 s22, s4, s23
	v_lshl_add_u64 v[6:7], v[6:7], 1, s[50:51]
	v_add_u32_e32 v0, 0xf0, v0
	s_add_u32 s48, s9, s10
	global_load_dwordx4 v[134:137], v[6:7], off
	v_lshl_add_u64 v[6:7], v[0:1], 1, s[50:51]
	v_ashrrev_i32_e32 v0, 3, v195
	v_readlane_b32 s9, v251, 38
	global_load_dwordx4 v[130:133], v[6:7], off
	s_addc_u32 s49, s22, s11
	v_lshl_add_u32 v6, v0, 11, s9
	v_xor_b32_e32 v0, v0, v195
	v_lshlrev_b32_e32 v0, 3, v0
	v_ashrrev_i32_e32 v204, 4, v195
	v_and_or_b32 v0, v0, 56, v6
	v_readlane_b32 s9, v251, 8
	s_waitcnt vmcnt(0)
	v_and_b32_e32 v205, 15, v195
	v_add_u32_e32 v6, s95, v204
	v_lshl_add_u32 v9, v204, 11, s9
	v_lshl_add_u64 v[200:201], v[0:1], 1, s[48:49]
	s_mov_b32 s9, m0
	s_mov_b32 m0, s0
	s_nop 0
	global_load_lds_dwordx4 v[200:201], off
	s_mov_b32 m0, s9
	s_mov_b64 s[10:11], 0x40000
	v_bitop3_b32 v8, v6, v205, 7 bitop3:0x6c
	v_lshl_add_u64 v[6:7], v[200:201], 0, s[10:11]
	s_add_i32 s22, s0, 0x2000
	s_mov_b32 s9, m0
	s_mov_b32 m0, s22
	s_nop 0
	global_load_lds_dwordx4 v[6:7], off
	s_mov_b32 m0, s9
	s_mov_b64 s[10:11], 0x80000
	v_lshl_add_u64 v[6:7], v[200:201], 0, s[10:11]
	s_add_i32 s23, s0, 0x4000
	s_mov_b32 s9, m0
	s_mov_b32 m0, s23
	s_nop 0
	global_load_lds_dwordx4 v[6:7], off
	s_mov_b32 m0, s9
	s_mov_b64 s[10:11], 0xc0000
	v_lshl_add_u64 v[6:7], v[200:201], 0, s[10:11]
	s_add_i32 s26, s0, 0x6000
	s_mov_b32 s9, m0
	s_mov_b32 m0, s26
	s_nop 0
	global_load_lds_dwordx4 v[6:7], off
	s_mov_b32 m0, s9
	v_lshl_add_u64 v[6:7], v[200:201], 0, s[12:13]
	s_mov_b32 s9, m0
	s_mov_b32 m0, s27
	s_nop 0
	global_load_lds_dwordx4 v[6:7], off
	s_mov_b32 m0, s9
	s_mov_b64 s[10:11], 0x40080
	v_lshl_add_u64 v[6:7], v[200:201], 0, s[10:11]
	s_add_i32 s9, s0, 0xa000
	s_mov_b32 s10, m0
	s_mov_b32 m0, s9
	s_nop 0
	global_load_lds_dwordx4 v[6:7], off
	s_mov_b32 m0, s10
	s_mov_b64 s[10:11], 0x80080
	v_lshl_add_u64 v[6:7], v[200:201], 0, s[10:11]
	s_add_i32 s10, s0, 0xc000
	s_mov_b32 s11, m0
	s_mov_b32 m0, s10
	s_nop 0
	global_load_lds_dwordx4 v[6:7], off
	s_mov_b32 m0, s11
	s_mov_b64 s[38:39], 0xc0080
	v_lshl_add_u64 v[6:7], v[200:201], 0, s[38:39]
	s_add_i32 s11, s0, 0xe000
	s_mov_b32 s38, m0
	s_mov_b32 m0, s11
	s_nop 0
	global_load_lds_dwordx4 v[6:7], off
	s_mov_b32 m0, s38
	v_lshl_or_b32 v0, v8, 3, v9
	s_waitcnt vmcnt(4) lgkmcnt(0)
	s_barrier
	v_lshl_add_u64 v[196:197], v[0:1], 1, s[48:49]
	s_mov_b64 s[38:39], 0x800
	v_lshl_add_u64 v[198:199], v[196:197], 0, s[38:39]
	v_lshl_add_u64 v[6:7], v[200:201], 0, s[24:25]
	s_add_i32 s38, s0, 0x10000
	s_mov_b32 s39, m0
	s_mov_b32 m0, s38
	s_nop 0
	global_load_lds_dwordx4 v[6:7], off
	s_mov_b32 m0, s39
	s_mov_b64 s[48:49], 0x40100
	v_lshl_add_u64 v[6:7], v[200:201], 0, s[48:49]
	s_add_i32 s39, s0, 0x12000
	s_mov_b32 s41, m0
	s_mov_b32 m0, s39
	s_nop 0
	global_load_lds_dwordx4 v[6:7], off
	s_mov_b32 m0, s41
	s_mov_b64 s[48:49], 0x80100
	v_bitop3_b32 v0, v202, v195, 7 bitop3:0x78
	v_lshl_add_u32 v190, v203, 7, 0
	v_lshl_add_u64 v[6:7], v[200:201], 0, s[48:49]
	s_add_i32 s41, s0, 0x14000
	s_mov_b32 s43, m0
	s_mov_b32 m0, s41
	s_nop 0
	global_load_lds_dwordx4 v[6:7], off
	s_mov_b32 m0, s43
	s_mov_b64 s[48:49], 0xc0100
	v_lshlrev_b32_e32 v191, 4, v0
	v_lshl_add_u64 v[6:7], v[200:201], 0, s[48:49]
	s_add_i32 s43, s0, 0x16000
	s_mov_b32 s45, m0
	s_mov_b32 m0, s43
	s_nop 0
	global_load_lds_dwordx4 v[6:7], off
	s_mov_b32 m0, s45
	v_add_u32_e32 v0, v190, v191
	ds_read_b128 v[206:209], v0
	ds_read_b128 v[214:217], v0 offset:4096
	ds_read_b128 v[234:237], v0 offset:8192
	ds_read_b128 v[240:243], v0 offset:12288
	ds_read_b128 v[244:247], v0 offset:16384
	ds_read_b128 v[6:9], v0 offset:20480
	s_waitcnt vmcnt(15) lgkmcnt(5)
	v_mfma_f32_32x32x16_bf16 v[114:129], v[206:209], v[2:5], 0
	ds_read_b128 v[206:209], v0 offset:24576
	s_waitcnt lgkmcnt(5)
	v_mfma_f32_32x32x16_bf16 v[98:113], v[214:217], v[2:5], 0
	ds_read_b128 v[214:217], v0 offset:28672
	s_waitcnt lgkmcnt(5)
	v_mfma_f32_32x32x16_bf16 v[82:97], v[234:237], v[2:5], 0
	s_waitcnt lgkmcnt(4)
	v_mfma_f32_32x32x16_bf16 v[66:81], v[240:243], v[2:5], 0
	s_waitcnt lgkmcnt(3)
	v_mfma_f32_32x32x16_bf16 v[50:65], v[244:247], v[2:5], 0
	s_waitcnt lgkmcnt(2)
	v_mfma_f32_32x32x16_bf16 v[34:49], v[6:9], v[2:5], 0
	s_waitcnt lgkmcnt(1)
	v_mfma_f32_32x32x16_bf16 v[18:33], v[206:209], v[2:5], 0
	s_waitcnt lgkmcnt(0)
	v_mfma_f32_32x32x16_bf16 v[2:17], v[214:217], v[2:5], 0
	v_add_u32_e32 v192, 2, v202
	v_bitop3_b32 v192, v192, v195, 7 bitop3:0x78
	v_lshlrev_b32_e32 v192, 4, v192
	v_add_u32_e32 v228, v190, v192
	ds_read_b128 v[206:209], v228
	ds_read_b128 v[214:217], v228 offset:4096
	ds_read_b128 v[234:237], v228 offset:8192
	ds_read_b128 v[240:243], v228 offset:12288
	ds_read_b128 v[244:247], v228 offset:16384
	ds_read_b128 v[230:233], v228 offset:20480
	s_waitcnt vmcnt(14) lgkmcnt(5)
	v_mfma_f32_32x32x16_bf16 v[114:129], v[206:209], v[186:189], v[114:129]
	ds_read_b128 v[206:209], v228 offset:24576
	s_waitcnt lgkmcnt(5)
	v_mfma_f32_32x32x16_bf16 v[98:113], v[214:217], v[186:189], v[98:113]
	ds_read_b128 v[214:217], v228 offset:28672
	s_waitcnt lgkmcnt(5)
	v_mfma_f32_32x32x16_bf16 v[82:97], v[234:237], v[186:189], v[82:97]
	s_waitcnt lgkmcnt(4)
	v_mfma_f32_32x32x16_bf16 v[66:81], v[240:243], v[186:189], v[66:81]
	s_waitcnt lgkmcnt(3)
	v_mfma_f32_32x32x16_bf16 v[50:65], v[244:247], v[186:189], v[50:65]
	s_waitcnt lgkmcnt(2)
	v_mfma_f32_32x32x16_bf16 v[34:49], v[230:233], v[186:189], v[34:49]
	s_waitcnt lgkmcnt(1)
	v_mfma_f32_32x32x16_bf16 v[18:33], v[206:209], v[186:189], v[18:33]
	s_waitcnt lgkmcnt(0)
	v_mfma_f32_32x32x16_bf16 v[2:17], v[214:217], v[186:189], v[2:17]
	v_add_u32_e32 v186, 4, v202
	v_bitop3_b32 v186, v186, v195, 7 bitop3:0x78
	v_lshlrev_b32_e32 v187, 4, v186
	v_add_u32_e32 v186, v190, v187
	ds_read_b128 v[206:209], v186
	ds_read_b128 v[214:217], v186 offset:4096
	ds_read_b128 v[234:237], v186 offset:8192
	ds_read_b128 v[240:243], v186 offset:12288
	ds_read_b128 v[244:247], v186 offset:16384
	ds_read_b128 v[230:233], v186 offset:20480
	s_waitcnt vmcnt(13) lgkmcnt(5)
	v_mfma_f32_32x32x16_bf16 v[114:129], v[206:209], v[182:185], v[114:129]
	ds_read_b128 v[206:209], v186 offset:24576
	s_waitcnt lgkmcnt(5)
	v_mfma_f32_32x32x16_bf16 v[98:113], v[214:217], v[182:185], v[98:113]
	ds_read_b128 v[214:217], v186 offset:28672
	s_waitcnt lgkmcnt(5)
	v_mfma_f32_32x32x16_bf16 v[82:97], v[234:237], v[182:185], v[82:97]
	s_waitcnt lgkmcnt(4)
	v_mfma_f32_32x32x16_bf16 v[66:81], v[240:243], v[182:185], v[66:81]
	s_waitcnt lgkmcnt(3)
	v_mfma_f32_32x32x16_bf16 v[50:65], v[244:247], v[182:185], v[50:65]
	s_waitcnt lgkmcnt(2)
	v_mfma_f32_32x32x16_bf16 v[34:49], v[230:233], v[182:185], v[34:49]
	s_waitcnt lgkmcnt(1)
	v_mfma_f32_32x32x16_bf16 v[18:33], v[206:209], v[182:185], v[18:33]
	s_waitcnt lgkmcnt(0)
	v_mfma_f32_32x32x16_bf16 v[2:17], v[214:217], v[182:185], v[2:17]
	v_add_u32_e32 v182, 6, v202
	v_bitop3_b32 v182, v182, v195, 7 bitop3:0x78
	v_lshlrev_b32_e32 v183, 4, v182
	v_add_u32_e32 v182, v190, v183
	ds_read_b128 v[206:209], v182
	ds_read_b128 v[214:217], v182 offset:4096
	ds_read_b128 v[234:237], v182 offset:8192
	ds_read_b128 v[240:243], v182 offset:12288
	ds_read_b128 v[244:247], v182 offset:16384
	ds_read_b128 v[230:233], v182 offset:20480
	s_waitcnt vmcnt(12) lgkmcnt(5)
	v_mfma_f32_32x32x16_bf16 v[114:129], v[206:209], v[178:181], v[114:129]
	ds_read_b128 v[206:209], v182 offset:24576
	s_waitcnt lgkmcnt(5)
	v_mfma_f32_32x32x16_bf16 v[98:113], v[214:217], v[178:181], v[98:113]
	ds_read_b128 v[214:217], v182 offset:28672
	s_waitcnt lgkmcnt(5)
	v_mfma_f32_32x32x16_bf16 v[82:97], v[234:237], v[178:181], v[82:97]
	s_waitcnt lgkmcnt(4)
	v_mfma_f32_32x32x16_bf16 v[66:81], v[240:243], v[178:181], v[66:81]
	s_waitcnt lgkmcnt(3)
	v_mfma_f32_32x32x16_bf16 v[50:65], v[244:247], v[178:181], v[50:65]
	s_waitcnt lgkmcnt(2)
	v_mfma_f32_32x32x16_bf16 v[34:49], v[230:233], v[178:181], v[34:49]
	s_waitcnt lgkmcnt(1)
	v_mfma_f32_32x32x16_bf16 v[18:33], v[206:209], v[178:181], v[18:33]
	s_waitcnt lgkmcnt(0)
	v_mfma_f32_32x32x16_bf16 v[2:17], v[214:217], v[178:181], v[2:17]
	s_waitcnt vmcnt(4) lgkmcnt(0)
	s_barrier
	s_mov_b64 s[48:49], 0x180
	v_lshl_add_u64 v[178:179], v[200:201], 0, s[48:49]
	s_mov_b32 s45, m0
	s_mov_b32 m0, s0
	s_nop 0
	global_load_lds_dwordx4 v[178:179], off
	s_mov_b32 m0, s45
	s_mov_b64 s[48:49], 0x40180
	v_lshl_add_u64 v[178:179], v[200:201], 0, s[48:49]
	s_mov_b32 s45, m0
	s_mov_b32 m0, s22
	s_nop 0
	global_load_lds_dwordx4 v[178:179], off
	s_mov_b32 m0, s45
	s_mov_b64 s[48:49], 0x80180
	v_lshl_add_u64 v[178:179], v[200:201], 0, s[48:49]
	s_mov_b32 s45, m0
	s_mov_b32 m0, s23
	s_nop 0
	global_load_lds_dwordx4 v[178:179], off
	s_mov_b32 m0, s45
	s_mov_b64 s[48:49], 0xc0180
	v_lshl_add_u64 v[178:179], v[200:201], 0, s[48:49]
	s_mov_b32 s45, m0
	s_mov_b32 m0, s26
	s_nop 0
	global_load_lds_dwordx4 v[178:179], off
	s_mov_b32 m0, s45
	ds_read_b128 v[206:209], v0 offset:32768
	ds_read_b128 v[214:217], v0 offset:36864
	ds_read_b128 v[234:237], v0 offset:40960
	ds_read_b128 v[240:243], v0 offset:45056
	ds_read_b128 v[244:247], v0 offset:49152
	ds_read_b128 v[178:181], v0 offset:53248
	s_waitcnt vmcnt(11) lgkmcnt(5)
	v_mfma_f32_32x32x16_bf16 v[114:129], v[206:209], v[174:177], v[114:129]
	ds_read_b128 v[206:209], v0 offset:57344
	s_waitcnt lgkmcnt(5)
	v_mfma_f32_32x32x16_bf16 v[98:113], v[214:217], v[174:177], v[98:113]
	ds_read_b128 v[214:217], v0 offset:61440
	s_waitcnt lgkmcnt(5)
	v_mfma_f32_32x32x16_bf16 v[82:97], v[234:237], v[174:177], v[82:97]
	s_waitcnt lgkmcnt(4)
	v_mfma_f32_32x32x16_bf16 v[66:81], v[240:243], v[174:177], v[66:81]
	s_waitcnt lgkmcnt(3)
	v_mfma_f32_32x32x16_bf16 v[50:65], v[244:247], v[174:177], v[50:65]
	s_waitcnt lgkmcnt(2)
	v_mfma_f32_32x32x16_bf16 v[34:49], v[178:181], v[174:177], v[34:49]
	s_waitcnt lgkmcnt(1)
	v_mfma_f32_32x32x16_bf16 v[18:33], v[206:209], v[174:177], v[18:33]
	s_waitcnt lgkmcnt(0)
	v_mfma_f32_32x32x16_bf16 v[2:17], v[214:217], v[174:177], v[2:17]
	ds_read_b128 v[206:209], v228 offset:32768
	ds_read_b128 v[214:217], v228 offset:36864
	ds_read_b128 v[234:237], v228 offset:40960
	ds_read_b128 v[240:243], v228 offset:45056
	ds_read_b128 v[244:247], v228 offset:49152
	ds_read_b128 v[174:177], v228 offset:53248
	s_waitcnt vmcnt(10) lgkmcnt(5)
	v_mfma_f32_32x32x16_bf16 v[114:129], v[206:209], v[170:173], v[114:129]
	ds_read_b128 v[206:209], v228 offset:57344
	s_waitcnt lgkmcnt(5)
	v_mfma_f32_32x32x16_bf16 v[98:113], v[214:217], v[170:173], v[98:113]
	ds_read_b128 v[214:217], v228 offset:61440
	s_waitcnt lgkmcnt(5)
	v_mfma_f32_32x32x16_bf16 v[82:97], v[234:237], v[170:173], v[82:97]
	s_waitcnt lgkmcnt(4)
	v_mfma_f32_32x32x16_bf16 v[66:81], v[240:243], v[170:173], v[66:81]
	s_waitcnt lgkmcnt(3)
	v_mfma_f32_32x32x16_bf16 v[50:65], v[244:247], v[170:173], v[50:65]
	s_waitcnt lgkmcnt(2)
	v_mfma_f32_32x32x16_bf16 v[34:49], v[174:177], v[170:173], v[34:49]
	s_waitcnt lgkmcnt(1)
	v_mfma_f32_32x32x16_bf16 v[18:33], v[206:209], v[170:173], v[18:33]
	s_waitcnt lgkmcnt(0)
	v_mfma_f32_32x32x16_bf16 v[2:17], v[214:217], v[170:173], v[2:17]
	ds_read_b128 v[206:209], v186 offset:32768
	ds_read_b128 v[214:217], v186 offset:36864
	ds_read_b128 v[234:237], v186 offset:40960
	ds_read_b128 v[240:243], v186 offset:45056
	ds_read_b128 v[244:247], v186 offset:49152
	ds_read_b128 v[170:173], v186 offset:53248
	s_waitcnt vmcnt(9) lgkmcnt(5)
	v_mfma_f32_32x32x16_bf16 v[114:129], v[206:209], v[166:169], v[114:129]
	ds_read_b128 v[206:209], v186 offset:57344
	s_waitcnt lgkmcnt(5)
	v_mfma_f32_32x32x16_bf16 v[98:113], v[214:217], v[166:169], v[98:113]
	ds_read_b128 v[214:217], v186 offset:61440
	s_waitcnt lgkmcnt(5)
	v_mfma_f32_32x32x16_bf16 v[82:97], v[234:237], v[166:169], v[82:97]
	s_waitcnt lgkmcnt(4)
	v_mfma_f32_32x32x16_bf16 v[66:81], v[240:243], v[166:169], v[66:81]
	s_waitcnt lgkmcnt(3)
	v_mfma_f32_32x32x16_bf16 v[50:65], v[244:247], v[166:169], v[50:65]
	s_waitcnt lgkmcnt(2)
	v_mfma_f32_32x32x16_bf16 v[34:49], v[170:173], v[166:169], v[34:49]
	s_waitcnt lgkmcnt(1)
	v_mfma_f32_32x32x16_bf16 v[18:33], v[206:209], v[166:169], v[18:33]
	s_waitcnt lgkmcnt(0)
	v_mfma_f32_32x32x16_bf16 v[2:17], v[214:217], v[166:169], v[2:17]
	ds_read_b128 v[206:209], v182 offset:32768
	ds_read_b128 v[214:217], v182 offset:36864
	ds_read_b128 v[234:237], v182 offset:40960
	ds_read_b128 v[240:243], v182 offset:45056
	ds_read_b128 v[244:247], v182 offset:49152
	ds_read_b128 v[166:169], v182 offset:53248
	s_waitcnt vmcnt(8) lgkmcnt(5)
	v_mfma_f32_32x32x16_bf16 v[114:129], v[206:209], v[162:165], v[114:129]
	ds_read_b128 v[206:209], v182 offset:57344
	s_waitcnt lgkmcnt(5)
	v_mfma_f32_32x32x16_bf16 v[98:113], v[214:217], v[162:165], v[98:113]
	ds_read_b128 v[214:217], v182 offset:61440
	s_waitcnt lgkmcnt(5)
	v_mfma_f32_32x32x16_bf16 v[82:97], v[234:237], v[162:165], v[82:97]
	s_waitcnt lgkmcnt(4)
	v_mfma_f32_32x32x16_bf16 v[66:81], v[240:243], v[162:165], v[66:81]
	s_waitcnt lgkmcnt(3)
	v_mfma_f32_32x32x16_bf16 v[50:65], v[244:247], v[162:165], v[50:65]
	s_waitcnt lgkmcnt(2)
	v_mfma_f32_32x32x16_bf16 v[34:49], v[166:169], v[162:165], v[34:49]
	s_waitcnt lgkmcnt(1)
	v_mfma_f32_32x32x16_bf16 v[18:33], v[206:209], v[162:165], v[18:33]
	s_waitcnt lgkmcnt(0)
	v_mfma_f32_32x32x16_bf16 v[2:17], v[214:217], v[162:165], v[2:17]
	s_waitcnt vmcnt(4) lgkmcnt(0)
	s_barrier
	s_mov_b32 s45, m0
	s_mov_b32 m0, s27
	s_nop 0
	global_load_lds_dwordx4 v[198:199], off
	s_mov_b32 m0, s45
	s_mov_b64 s[48:49], 0x20800
	v_lshl_add_u64 v[162:163], v[196:197], 0, s[48:49]
	s_mov_b32 s45, m0
	s_mov_b32 m0, s9
	s_nop 0
	global_load_lds_dwordx4 v[162:163], off
	s_mov_b32 m0, s45
	s_mov_b64 s[48:49], 0x40800
	v_lshl_add_u64 v[162:163], v[196:197], 0, s[48:49]
	s_mov_b32 s45, m0
	s_mov_b32 m0, s10
	s_nop 0
	global_load_lds_dwordx4 v[162:163], off
	s_mov_b32 m0, s45
	s_mov_b64 s[48:49], 0x60800
	v_add_u32_e32 v166, 0x10000, v190
	v_lshl_add_u64 v[162:163], v[196:197], 0, s[48:49]
	s_mov_b32 s45, m0
	s_mov_b32 m0, s11
	s_nop 0
	global_load_lds_dwordx4 v[162:163], off
	s_mov_b32 m0, s45
	v_add_u32_e32 v167, v166, v191
	ds_read_b128 v[206:209], v167
	ds_read_b128 v[214:217], v167 offset:4096
	ds_read_b128 v[234:237], v167 offset:8192
	ds_read_b128 v[240:243], v167 offset:12288
	ds_read_b128 v[244:247], v167 offset:16384
	ds_read_b128 v[162:165], v167 offset:20480
	s_waitcnt vmcnt(7) lgkmcnt(5)
	v_mfma_f32_32x32x16_bf16 v[114:129], v[206:209], v[158:161], v[114:129]
	ds_read_b128 v[206:209], v167 offset:24576
	s_waitcnt lgkmcnt(5)
	v_mfma_f32_32x32x16_bf16 v[98:113], v[214:217], v[158:161], v[98:113]
	ds_read_b128 v[214:217], v167 offset:28672
	s_waitcnt lgkmcnt(5)
	v_mfma_f32_32x32x16_bf16 v[82:97], v[234:237], v[158:161], v[82:97]
	s_waitcnt lgkmcnt(4)
	v_mfma_f32_32x32x16_bf16 v[66:81], v[240:243], v[158:161], v[66:81]
	s_waitcnt lgkmcnt(3)
	v_mfma_f32_32x32x16_bf16 v[50:65], v[244:247], v[158:161], v[50:65]
	s_waitcnt lgkmcnt(2)
	v_mfma_f32_32x32x16_bf16 v[34:49], v[162:165], v[158:161], v[34:49]
	s_waitcnt lgkmcnt(1)
	v_mfma_f32_32x32x16_bf16 v[18:33], v[206:209], v[158:161], v[18:33]
	s_waitcnt lgkmcnt(0)
	v_mfma_f32_32x32x16_bf16 v[2:17], v[214:217], v[158:161], v[2:17]
	v_add_u32_e32 v162, v166, v192
	ds_read_b128 v[206:209], v162
	ds_read_b128 v[214:217], v162 offset:4096
	ds_read_b128 v[234:237], v162 offset:8192
	ds_read_b128 v[240:243], v162 offset:12288
	ds_read_b128 v[244:247], v162 offset:16384
	ds_read_b128 v[158:161], v162 offset:20480
	s_waitcnt vmcnt(6) lgkmcnt(5)
	v_mfma_f32_32x32x16_bf16 v[114:129], v[206:209], v[154:157], v[114:129]
	ds_read_b128 v[206:209], v162 offset:24576
	s_waitcnt lgkmcnt(5)
	v_mfma_f32_32x32x16_bf16 v[98:113], v[214:217], v[154:157], v[98:113]
	ds_read_b128 v[214:217], v162 offset:28672
	s_waitcnt lgkmcnt(5)
	v_mfma_f32_32x32x16_bf16 v[82:97], v[234:237], v[154:157], v[82:97]
	s_waitcnt lgkmcnt(4)
	v_mfma_f32_32x32x16_bf16 v[66:81], v[240:243], v[154:157], v[66:81]
	s_waitcnt lgkmcnt(3)
	v_mfma_f32_32x32x16_bf16 v[50:65], v[244:247], v[154:157], v[50:65]
	s_waitcnt lgkmcnt(2)
	v_mfma_f32_32x32x16_bf16 v[34:49], v[158:161], v[154:157], v[34:49]
	s_waitcnt lgkmcnt(1)
	v_mfma_f32_32x32x16_bf16 v[18:33], v[206:209], v[154:157], v[18:33]
	s_waitcnt lgkmcnt(0)
	v_mfma_f32_32x32x16_bf16 v[2:17], v[214:217], v[154:157], v[2:17]
	v_add_u32_e32 v158, v166, v187
	ds_read_b128 v[206:209], v158
	ds_read_b128 v[214:217], v158 offset:4096
	ds_read_b128 v[234:237], v158 offset:8192
	ds_read_b128 v[240:243], v158 offset:12288
	ds_read_b128 v[244:247], v158 offset:16384
	ds_read_b128 v[154:157], v158 offset:20480
	s_waitcnt vmcnt(5) lgkmcnt(5)
	v_mfma_f32_32x32x16_bf16 v[114:129], v[206:209], v[150:153], v[114:129]
	ds_read_b128 v[206:209], v158 offset:24576
	s_waitcnt lgkmcnt(5)
	v_mfma_f32_32x32x16_bf16 v[98:113], v[214:217], v[150:153], v[98:113]
	ds_read_b128 v[214:217], v158 offset:28672
	s_waitcnt lgkmcnt(5)
	v_mfma_f32_32x32x16_bf16 v[82:97], v[234:237], v[150:153], v[82:97]
	s_waitcnt lgkmcnt(4)
	v_mfma_f32_32x32x16_bf16 v[66:81], v[240:243], v[150:153], v[66:81]
	s_waitcnt lgkmcnt(3)
	v_mfma_f32_32x32x16_bf16 v[50:65], v[244:247], v[150:153], v[50:65]
	s_waitcnt lgkmcnt(2)
	v_mfma_f32_32x32x16_bf16 v[34:49], v[154:157], v[150:153], v[34:49]
	s_waitcnt lgkmcnt(1)
	v_mfma_f32_32x32x16_bf16 v[18:33], v[206:209], v[150:153], v[18:33]
	s_waitcnt lgkmcnt(0)
	v_mfma_f32_32x32x16_bf16 v[2:17], v[214:217], v[150:153], v[2:17]
	v_add_u32_e32 v154, v166, v183
	ds_read_b128 v[206:209], v154
	ds_read_b128 v[214:217], v154 offset:4096
	ds_read_b128 v[234:237], v154 offset:8192
	ds_read_b128 v[240:243], v154 offset:12288
	ds_read_b128 v[244:247], v154 offset:16384
	ds_read_b128 v[150:153], v154 offset:20480
	s_waitcnt vmcnt(4) lgkmcnt(5)
	v_mfma_f32_32x32x16_bf16 v[114:129], v[206:209], v[146:149], v[114:129]
	ds_read_b128 v[206:209], v154 offset:24576
	s_waitcnt lgkmcnt(5)
	v_mfma_f32_32x32x16_bf16 v[98:113], v[214:217], v[146:149], v[98:113]
	ds_read_b128 v[214:217], v154 offset:28672
	s_waitcnt lgkmcnt(5)
	v_mfma_f32_32x32x16_bf16 v[82:97], v[234:237], v[146:149], v[82:97]
	s_waitcnt lgkmcnt(4)
	v_mfma_f32_32x32x16_bf16 v[66:81], v[240:243], v[146:149], v[66:81]
	s_waitcnt lgkmcnt(3)
	v_mfma_f32_32x32x16_bf16 v[50:65], v[244:247], v[146:149], v[50:65]
	s_waitcnt lgkmcnt(2)
	v_mfma_f32_32x32x16_bf16 v[34:49], v[150:153], v[146:149], v[34:49]
	s_waitcnt lgkmcnt(1)
	v_mfma_f32_32x32x16_bf16 v[18:33], v[206:209], v[146:149], v[18:33]
	s_waitcnt lgkmcnt(0)
	v_mfma_f32_32x32x16_bf16 v[2:17], v[214:217], v[146:149], v[2:17]
	s_waitcnt vmcnt(4) lgkmcnt(0)
	s_barrier
	s_mov_b64 s[48:49], 0x80800
	v_lshl_add_u64 v[146:147], v[196:197], 0, s[48:49]
	s_mov_b32 s45, m0
	s_mov_b32 m0, s38
	s_nop 0
	global_load_lds_dwordx4 v[146:147], off
	s_mov_b32 m0, s45
	s_mov_b64 s[48:49], 0xa0800
	v_lshl_add_u64 v[146:147], v[196:197], 0, s[48:49]
	s_mov_b32 s38, m0
	s_mov_b32 m0, s39
	s_nop 0
	global_load_lds_dwordx4 v[146:147], off
	s_mov_b32 m0, s38
	s_mov_b64 s[38:39], 0xc0800
	v_lshl_add_u64 v[146:147], v[196:197], 0, s[38:39]
	s_mov_b32 s38, m0
	s_mov_b32 m0, s41
	s_nop 0
	global_load_lds_dwordx4 v[146:147], off
	s_mov_b32 m0, s38
	s_mov_b64 s[38:39], 0xe0800
	v_lshl_add_u64 v[146:147], v[196:197], 0, s[38:39]
	s_mov_b32 s38, m0
	s_mov_b32 m0, s43
	s_nop 0
	global_load_lds_dwordx4 v[146:147], off
	s_mov_b32 m0, s38
	ds_read_b128 v[206:209], v0
	ds_read_b128 v[214:217], v0 offset:4096
	ds_read_b128 v[234:237], v0 offset:8192
	ds_read_b128 v[240:243], v0 offset:12288
	ds_read_b128 v[244:247], v0 offset:16384
	ds_read_b128 v[146:149], v0 offset:20480
	s_waitcnt vmcnt(3) lgkmcnt(5)
	v_mfma_f32_32x32x16_bf16 v[114:129], v[206:209], v[142:145], v[114:129]
	ds_read_b128 v[206:209], v0 offset:24576
	s_waitcnt lgkmcnt(5)
	v_mfma_f32_32x32x16_bf16 v[98:113], v[214:217], v[142:145], v[98:113]
	ds_read_b128 v[214:217], v0 offset:28672
	s_waitcnt lgkmcnt(5)
	v_mfma_f32_32x32x16_bf16 v[82:97], v[234:237], v[142:145], v[82:97]
	s_waitcnt lgkmcnt(4)
	v_mfma_f32_32x32x16_bf16 v[66:81], v[240:243], v[142:145], v[66:81]
	s_waitcnt lgkmcnt(3)
	v_mfma_f32_32x32x16_bf16 v[50:65], v[244:247], v[142:145], v[50:65]
	s_waitcnt lgkmcnt(2)
	v_mfma_f32_32x32x16_bf16 v[34:49], v[146:149], v[142:145], v[34:49]
	s_waitcnt lgkmcnt(1)
	v_mfma_f32_32x32x16_bf16 v[18:33], v[206:209], v[142:145], v[18:33]
	s_waitcnt lgkmcnt(0)
	v_mfma_f32_32x32x16_bf16 v[2:17], v[214:217], v[142:145], v[2:17]
	ds_read_b128 v[206:209], v228
	ds_read_b128 v[214:217], v228 offset:4096
	ds_read_b128 v[234:237], v228 offset:8192
	ds_read_b128 v[240:243], v228 offset:12288
	ds_read_b128 v[244:247], v228 offset:16384
	ds_read_b128 v[142:145], v228 offset:20480
	s_waitcnt vmcnt(2) lgkmcnt(5)
	v_mfma_f32_32x32x16_bf16 v[114:129], v[206:209], v[138:141], v[114:129]
	ds_read_b128 v[206:209], v228 offset:24576
	s_waitcnt lgkmcnt(5)
	v_mfma_f32_32x32x16_bf16 v[98:113], v[214:217], v[138:141], v[98:113]
	ds_read_b128 v[214:217], v228 offset:28672
	s_waitcnt lgkmcnt(5)
	v_mfma_f32_32x32x16_bf16 v[82:97], v[234:237], v[138:141], v[82:97]
	s_waitcnt lgkmcnt(4)
	v_mfma_f32_32x32x16_bf16 v[66:81], v[240:243], v[138:141], v[66:81]
	s_waitcnt lgkmcnt(3)
	v_mfma_f32_32x32x16_bf16 v[50:65], v[244:247], v[138:141], v[50:65]
	s_waitcnt lgkmcnt(2)
	v_mfma_f32_32x32x16_bf16 v[34:49], v[142:145], v[138:141], v[34:49]
	s_waitcnt lgkmcnt(1)
	v_mfma_f32_32x32x16_bf16 v[18:33], v[206:209], v[138:141], v[18:33]
	s_waitcnt lgkmcnt(0)
	v_mfma_f32_32x32x16_bf16 v[2:17], v[214:217], v[138:141], v[2:17]
	ds_read_b128 v[206:209], v186
	ds_read_b128 v[214:217], v186 offset:4096
	ds_read_b128 v[234:237], v186 offset:8192
	ds_read_b128 v[240:243], v186 offset:12288
	ds_read_b128 v[244:247], v186 offset:16384
	ds_read_b128 v[138:141], v186 offset:20480
	s_waitcnt vmcnt(1) lgkmcnt(5)
	v_mfma_f32_32x32x16_bf16 v[114:129], v[206:209], v[134:137], v[114:129]
	ds_read_b128 v[206:209], v186 offset:24576
	s_waitcnt lgkmcnt(5)
	v_mfma_f32_32x32x16_bf16 v[98:113], v[214:217], v[134:137], v[98:113]
	ds_read_b128 v[214:217], v186 offset:28672
	s_waitcnt lgkmcnt(5)
	v_mfma_f32_32x32x16_bf16 v[82:97], v[234:237], v[134:137], v[82:97]
	s_waitcnt lgkmcnt(4)
	v_mfma_f32_32x32x16_bf16 v[66:81], v[240:243], v[134:137], v[66:81]
	s_waitcnt lgkmcnt(3)
	v_mfma_f32_32x32x16_bf16 v[50:65], v[244:247], v[134:137], v[50:65]
	s_waitcnt lgkmcnt(2)
	v_mfma_f32_32x32x16_bf16 v[34:49], v[138:141], v[134:137], v[34:49]
	s_waitcnt lgkmcnt(1)
	v_mfma_f32_32x32x16_bf16 v[18:33], v[206:209], v[134:137], v[18:33]
	s_waitcnt lgkmcnt(0)
	v_mfma_f32_32x32x16_bf16 v[2:17], v[214:217], v[134:137], v[2:17]
	ds_read_b128 v[206:209], v182
	ds_read_b128 v[214:217], v182 offset:4096
	ds_read_b128 v[234:237], v182 offset:8192
	ds_read_b128 v[240:243], v182 offset:12288
	ds_read_b128 v[244:247], v182 offset:16384
	ds_read_b128 v[134:137], v182 offset:20480
	s_waitcnt vmcnt(0) lgkmcnt(5)
	v_mfma_f32_32x32x16_bf16 v[114:129], v[206:209], v[130:133], v[114:129]
	ds_read_b128 v[206:209], v182 offset:24576
	s_waitcnt lgkmcnt(5)
	v_mfma_f32_32x32x16_bf16 v[98:113], v[214:217], v[130:133], v[98:113]
	ds_read_b128 v[214:217], v182 offset:28672
	s_waitcnt lgkmcnt(5)
	v_mfma_f32_32x32x16_bf16 v[82:97], v[234:237], v[130:133], v[82:97]
	s_waitcnt lgkmcnt(4)
	v_mfma_f32_32x32x16_bf16 v[66:81], v[240:243], v[130:133], v[66:81]
	s_waitcnt lgkmcnt(3)
	v_mfma_f32_32x32x16_bf16 v[50:65], v[244:247], v[130:133], v[50:65]
	s_waitcnt lgkmcnt(2)
	v_mfma_f32_32x32x16_bf16 v[34:49], v[134:137], v[130:133], v[34:49]
	s_waitcnt lgkmcnt(1)
	v_mfma_f32_32x32x16_bf16 v[18:33], v[206:209], v[130:133], v[18:33]
	s_waitcnt lgkmcnt(0)
	v_mfma_f32_32x32x16_bf16 v[2:17], v[214:217], v[130:133], v[2:17]
	v_max_f32_e32 v0, v115, v115
	v_max_f32_e32 v130, v114, v114
	v_max_f32_e32 v0, v130, v0
	v_max3_f32 v0, v0, v116, v117
	v_max3_f32 v0, v0, v118, v119
	v_max3_f32 v0, v0, v120, v121
	v_max3_f32 v0, v0, v122, v123
	v_max3_f32 v0, v0, v124, v125
	v_max3_f32 v0, v0, v126, v127
	v_max3_f32 v0, v0, v128, v129
	v_max3_f32 v0, v0, v98, v99
	v_max3_f32 v0, v0, v100, v101
	v_max3_f32 v0, v0, v102, v103
	v_max3_f32 v0, v0, v104, v105
	v_max3_f32 v0, v0, v106, v107
	v_max3_f32 v0, v0, v108, v109
	v_max3_f32 v0, v0, v110, v111
	v_max3_f32 v0, v0, v112, v113
	v_max3_f32 v0, v0, v82, v83
	v_max3_f32 v0, v0, v84, v85
	v_max3_f32 v0, v0, v86, v87
	v_max3_f32 v0, v0, v88, v89
	v_max3_f32 v0, v0, v90, v91
	v_max3_f32 v0, v0, v92, v93
	v_max3_f32 v0, v0, v94, v95
	v_max3_f32 v0, v0, v96, v97
	v_max3_f32 v0, v0, v66, v67
	v_max3_f32 v0, v0, v68, v69
	v_max3_f32 v0, v0, v70, v71
	v_max3_f32 v0, v0, v72, v73
	v_max3_f32 v0, v0, v74, v75
	v_max3_f32 v0, v0, v76, v77
	v_max3_f32 v0, v0, v78, v79
	v_max3_f32 v0, v0, v80, v81
	v_max3_f32 v0, v0, v50, v51
	v_max3_f32 v0, v0, v52, v53
	v_max3_f32 v0, v0, v54, v55
	v_max3_f32 v0, v0, v56, v57
	v_max3_f32 v0, v0, v58, v59
	v_max3_f32 v0, v0, v60, v61
	v_max3_f32 v0, v0, v62, v63
	v_max3_f32 v0, v0, v64, v65
	v_max3_f32 v0, v0, v34, v35
	v_max3_f32 v0, v0, v36, v37
	v_max3_f32 v0, v0, v38, v39
	v_max3_f32 v0, v0, v40, v41
	v_max3_f32 v0, v0, v42, v43
	v_max3_f32 v0, v0, v44, v45
	v_max3_f32 v0, v0, v46, v47
	v_max3_f32 v0, v0, v48, v49
	v_max3_f32 v0, v0, v18, v19
	v_max3_f32 v0, v0, v20, v21
	v_max3_f32 v0, v0, v22, v23
	v_max3_f32 v0, v0, v24, v25
	v_max3_f32 v0, v0, v26, v27
	v_max3_f32 v0, v0, v28, v29
	v_max3_f32 v0, v0, v30, v31
	v_max3_f32 v0, v0, v32, v33
	v_max3_f32 v0, v0, v2, v3
	v_max3_f32 v0, v0, v4, v5
	v_max3_f32 v0, v0, v6, v7
	v_max3_f32 v0, v0, v8, v9
	v_max3_f32 v0, v0, v10, v11
	v_max3_f32 v0, v0, v12, v13
	v_cmp_lt_i32_e32 vcc, v219, v213
	v_max3_f32 v0, v0, v14, v15
	v_max3_f32 v0, v0, v16, v17
	v_cndmask_b32_e32 v130, v211, v219, vcc
	v_lshlrev_b32_e32 v133, 2, v130
	ds_bpermute_b32 v130, v133, v0
	s_waitcnt vmcnt(4) lgkmcnt(0)
	s_barrier
	v_cmp_gt_u32_e32 vcc, 32, v195
	s_waitcnt lgkmcnt(0)
	v_max_f32_e32 v130, v130, v130
	v_max_f32_e32 v134, v0, v130
	v_sub_f32_e32 v0, v114, v134
	v_exp_f32_e32 v0, v0
	v_sub_f32_e32 v114, v115, v134
	v_exp_f32_e32 v114, v114
	v_sub_f32_e32 v115, v116, v134
	v_exp_f32_e32 v115, v115
	v_sub_f32_e32 v116, v117, v134
	v_exp_f32_e32 v116, v116
	v_add_f32_e32 v117, 0, v0
	v_add_f32_e32 v117, v114, v117
	v_add_f32_e32 v117, v115, v117
	v_add_f32_e32 v130, v116, v117
	v_sub_f32_e32 v117, v118, v134
	v_exp_f32_e32 v117, v117
	v_sub_f32_e32 v118, v119, v134
	v_exp_f32_e32 v118, v118
	v_sub_f32_e32 v119, v120, v134
	v_exp_f32_e32 v119, v119
	v_sub_f32_e32 v120, v121, v134
	v_exp_f32_e32 v120, v120
	v_add_f32_e32 v121, v117, v130
	v_add_f32_e32 v121, v118, v121
	v_add_f32_e32 v121, v119, v121
	v_add_f32_e32 v130, v120, v121
	v_sub_f32_e32 v121, v122, v134
	v_exp_f32_e32 v121, v121
	v_sub_f32_e32 v122, v123, v134
	v_exp_f32_e32 v122, v122
	v_sub_f32_e32 v123, v124, v134
	v_exp_f32_e32 v123, v123
	v_sub_f32_e32 v124, v125, v134
	v_exp_f32_e32 v124, v124
	v_add_f32_e32 v125, v121, v130
	v_add_f32_e32 v125, v122, v125
	v_add_f32_e32 v125, v123, v125
	v_add_f32_e32 v135, v124, v125
	v_sub_f32_e32 v125, v126, v134
	v_exp_f32_e32 v125, v125
	v_sub_f32_e32 v126, v127, v134
	v_exp_f32_e32 v130, v126
	v_sub_f32_e32 v126, v128, v134
	v_exp_f32_e32 v131, v126
	v_sub_f32_e32 v126, v129, v134
	v_exp_f32_e32 v132, v126
	v_sub_f32_e32 v98, v98, v134
	v_add_f32_e32 v126, v125, v135
	v_exp_f32_e32 v98, v98
	v_sub_f32_e32 v99, v99, v134
	v_add_f32_e32 v126, v130, v126
	v_exp_f32_e32 v99, v99
	v_sub_f32_e32 v100, v100, v134
	v_add_f32_e32 v126, v131, v126
	v_exp_f32_e32 v100, v100
	v_sub_f32_e32 v101, v101, v134
	v_add_f32_e32 v126, v132, v126
	v_exp_f32_e32 v101, v101
	v_sub_f32_e32 v102, v102, v134
	v_add_f32_e32 v126, v98, v126
	v_exp_f32_e32 v102, v102
	v_sub_f32_e32 v103, v103, v134
	v_add_f32_e32 v126, v99, v126
	v_exp_f32_e32 v103, v103
	v_sub_f32_e32 v104, v104, v134
	v_add_f32_e32 v126, v100, v126
	v_exp_f32_e32 v104, v104
	v_sub_f32_e32 v105, v105, v134
	v_add_f32_e32 v126, v101, v126
	v_exp_f32_e32 v105, v105
	v_sub_f32_e32 v106, v106, v134
	v_add_f32_e32 v126, v102, v126
	v_exp_f32_e32 v106, v106
	v_sub_f32_e32 v107, v107, v134
	v_add_f32_e32 v126, v103, v126
	v_exp_f32_e32 v107, v107
	v_sub_f32_e32 v108, v108, v134
	v_add_f32_e32 v126, v104, v126
	v_exp_f32_e32 v108, v108
	v_sub_f32_e32 v109, v109, v134
	v_add_f32_e32 v126, v105, v126
	v_exp_f32_e32 v109, v109
	v_sub_f32_e32 v110, v110, v134
	v_add_f32_e32 v126, v106, v126
	v_exp_f32_e32 v110, v110
	v_sub_f32_e32 v111, v111, v134
	v_add_f32_e32 v126, v107, v126
	v_exp_f32_e32 v111, v111
	v_sub_f32_e32 v112, v112, v134
	v_add_f32_e32 v126, v108, v126
	v_exp_f32_e32 v112, v112
	v_sub_f32_e32 v113, v113, v134
	v_add_f32_e32 v126, v109, v126
	v_exp_f32_e32 v113, v113
	v_sub_f32_e32 v82, v82, v134
	v_add_f32_e32 v126, v110, v126
	v_exp_f32_e32 v82, v82
	v_sub_f32_e32 v83, v83, v134
	v_add_f32_e32 v126, v111, v126
	v_exp_f32_e32 v83, v83
	v_sub_f32_e32 v84, v84, v134
	v_add_f32_e32 v126, v112, v126
	v_exp_f32_e32 v84, v84
	v_sub_f32_e32 v85, v85, v134
	v_add_f32_e32 v126, v113, v126
	v_exp_f32_e32 v85, v85
	v_sub_f32_e32 v86, v86, v134
	v_add_f32_e32 v126, v82, v126
	v_exp_f32_e32 v86, v86
	v_sub_f32_e32 v87, v87, v134
	v_add_f32_e32 v126, v83, v126
	v_exp_f32_e32 v87, v87
	v_sub_f32_e32 v88, v88, v134
	v_add_f32_e32 v126, v84, v126
	v_exp_f32_e32 v88, v88
	v_sub_f32_e32 v89, v89, v134
	v_add_f32_e32 v126, v85, v126
	v_exp_f32_e32 v89, v89
	v_sub_f32_e32 v90, v90, v134
	v_add_f32_e32 v126, v86, v126
	v_exp_f32_e32 v90, v90
	v_sub_f32_e32 v91, v91, v134
	v_add_f32_e32 v126, v87, v126
	v_exp_f32_e32 v91, v91
	v_sub_f32_e32 v92, v92, v134
	v_add_f32_e32 v126, v88, v126
	v_exp_f32_e32 v92, v92
	v_sub_f32_e32 v93, v93, v134
	v_add_f32_e32 v126, v89, v126
	v_exp_f32_e32 v93, v93
	v_sub_f32_e32 v94, v94, v134
	v_add_f32_e32 v126, v90, v126
	v_exp_f32_e32 v94, v94
	v_sub_f32_e32 v95, v95, v134
	v_add_f32_e32 v126, v91, v126
	v_exp_f32_e32 v95, v95
	v_sub_f32_e32 v96, v96, v134
	v_add_f32_e32 v126, v92, v126
	v_exp_f32_e32 v96, v96
	v_sub_f32_e32 v97, v97, v134
	v_add_f32_e32 v126, v93, v126
	v_exp_f32_e32 v97, v97
	v_sub_f32_e32 v66, v66, v134
	v_add_f32_e32 v126, v94, v126
	v_exp_f32_e32 v66, v66
	v_sub_f32_e32 v67, v67, v134
	v_add_f32_e32 v126, v95, v126
	v_exp_f32_e32 v67, v67
	v_sub_f32_e32 v68, v68, v134
	v_add_f32_e32 v126, v96, v126
	v_exp_f32_e32 v68, v68
	v_sub_f32_e32 v69, v69, v134
	v_add_f32_e32 v126, v97, v126
	v_exp_f32_e32 v69, v69
	v_sub_f32_e32 v70, v70, v134
	v_add_f32_e32 v126, v66, v126
	v_exp_f32_e32 v70, v70
	v_sub_f32_e32 v71, v71, v134
	v_add_f32_e32 v126, v67, v126
	v_exp_f32_e32 v71, v71
	v_sub_f32_e32 v72, v72, v134
	v_add_f32_e32 v126, v68, v126
	v_exp_f32_e32 v72, v72
	v_sub_f32_e32 v73, v73, v134
	v_add_f32_e32 v126, v69, v126
	v_exp_f32_e32 v73, v73
	v_sub_f32_e32 v74, v74, v134
	v_add_f32_e32 v126, v70, v126
	v_exp_f32_e32 v74, v74
	v_sub_f32_e32 v75, v75, v134
	v_add_f32_e32 v126, v71, v126
	v_exp_f32_e32 v75, v75
	v_sub_f32_e32 v76, v76, v134
	v_add_f32_e32 v126, v72, v126
	v_exp_f32_e32 v76, v76
	v_sub_f32_e32 v77, v77, v134
	v_add_f32_e32 v126, v73, v126
	v_exp_f32_e32 v77, v77
	v_sub_f32_e32 v78, v78, v134
	v_add_f32_e32 v126, v74, v126
	v_exp_f32_e32 v78, v78
	v_sub_f32_e32 v79, v79, v134
	v_add_f32_e32 v126, v75, v126
	v_exp_f32_e32 v79, v79
	v_sub_f32_e32 v80, v80, v134
	v_add_f32_e32 v126, v76, v126
	v_exp_f32_e32 v80, v80
	v_sub_f32_e32 v81, v81, v134
	v_add_f32_e32 v126, v77, v126
	v_exp_f32_e32 v81, v81
	v_sub_f32_e32 v50, v50, v134
	v_add_f32_e32 v126, v78, v126
	v_exp_f32_e32 v50, v50
	v_sub_f32_e32 v51, v51, v134
	v_add_f32_e32 v126, v79, v126
	v_exp_f32_e32 v51, v51
	v_sub_f32_e32 v52, v52, v134
	v_add_f32_e32 v126, v80, v126
	v_exp_f32_e32 v52, v52
	v_sub_f32_e32 v53, v53, v134
	v_add_f32_e32 v126, v81, v126
	v_exp_f32_e32 v53, v53
	v_sub_f32_e32 v54, v54, v134
	v_add_f32_e32 v126, v50, v126
	v_exp_f32_e32 v54, v54
	v_sub_f32_e32 v55, v55, v134
	v_add_f32_e32 v126, v51, v126
	v_exp_f32_e32 v55, v55
	v_sub_f32_e32 v56, v56, v134
	v_add_f32_e32 v126, v52, v126
	v_exp_f32_e32 v56, v56
	v_sub_f32_e32 v57, v57, v134
	v_add_f32_e32 v126, v53, v126
	v_exp_f32_e32 v57, v57
	v_sub_f32_e32 v58, v58, v134
	v_add_f32_e32 v126, v54, v126
	v_exp_f32_e32 v58, v58
	v_sub_f32_e32 v59, v59, v134
	v_add_f32_e32 v126, v55, v126
	v_exp_f32_e32 v59, v59
	v_sub_f32_e32 v60, v60, v134
	v_add_f32_e32 v126, v56, v126
	v_exp_f32_e32 v60, v60
	v_sub_f32_e32 v61, v61, v134
	v_add_f32_e32 v126, v57, v126
	v_exp_f32_e32 v61, v61
	v_sub_f32_e32 v62, v62, v134
	v_add_f32_e32 v126, v58, v126
	v_exp_f32_e32 v62, v62
	v_sub_f32_e32 v63, v63, v134
	v_add_f32_e32 v126, v59, v126
	v_exp_f32_e32 v63, v63
	v_sub_f32_e32 v64, v64, v134
	v_add_f32_e32 v126, v60, v126
	v_exp_f32_e32 v64, v64
	v_sub_f32_e32 v65, v65, v134
	v_add_f32_e32 v126, v61, v126
	v_exp_f32_e32 v65, v65
	v_sub_f32_e32 v34, v34, v134
	v_add_f32_e32 v126, v62, v126
	v_exp_f32_e32 v34, v34
	v_sub_f32_e32 v35, v35, v134
	v_add_f32_e32 v126, v63, v126
	v_exp_f32_e32 v35, v35
	v_sub_f32_e32 v36, v36, v134
	v_add_f32_e32 v126, v64, v126
	v_exp_f32_e32 v36, v36
	v_sub_f32_e32 v37, v37, v134
	v_add_f32_e32 v126, v65, v126
	v_exp_f32_e32 v37, v37
	v_sub_f32_e32 v38, v38, v134
	v_add_f32_e32 v126, v34, v126
	v_exp_f32_e32 v38, v38
	v_sub_f32_e32 v39, v39, v134
	v_add_f32_e32 v126, v35, v126
	v_exp_f32_e32 v39, v39
	v_sub_f32_e32 v40, v40, v134
	v_add_f32_e32 v126, v36, v126
	v_exp_f32_e32 v40, v40
	v_sub_f32_e32 v41, v41, v134
	v_add_f32_e32 v126, v37, v126
	v_exp_f32_e32 v41, v41
	v_sub_f32_e32 v42, v42, v134
	v_add_f32_e32 v126, v38, v126
	v_exp_f32_e32 v42, v42
	v_sub_f32_e32 v43, v43, v134
	v_add_f32_e32 v126, v39, v126
	v_exp_f32_e32 v43, v43
	v_sub_f32_e32 v44, v44, v134
	v_add_f32_e32 v126, v40, v126
	v_exp_f32_e32 v44, v44
	v_sub_f32_e32 v45, v45, v134
	v_add_f32_e32 v126, v41, v126
	v_exp_f32_e32 v45, v45
	v_sub_f32_e32 v46, v46, v134
	v_add_f32_e32 v126, v42, v126
	v_exp_f32_e32 v46, v46
	v_sub_f32_e32 v47, v47, v134
	v_add_f32_e32 v126, v43, v126
	v_exp_f32_e32 v47, v47
	v_sub_f32_e32 v48, v48, v134
	v_add_f32_e32 v126, v44, v126
	v_exp_f32_e32 v48, v48
	v_sub_f32_e32 v49, v49, v134
	v_add_f32_e32 v126, v45, v126
	v_exp_f32_e32 v49, v49
	v_sub_f32_e32 v18, v18, v134
	v_add_f32_e32 v126, v46, v126
	v_exp_f32_e32 v18, v18
	v_sub_f32_e32 v19, v19, v134
	v_add_f32_e32 v126, v47, v126
	v_exp_f32_e32 v19, v19
	v_sub_f32_e32 v20, v20, v134
	v_add_f32_e32 v126, v48, v126
	v_exp_f32_e32 v20, v20
	v_sub_f32_e32 v21, v21, v134
	v_add_f32_e32 v126, v49, v126
	v_exp_f32_e32 v21, v21
	v_sub_f32_e32 v22, v22, v134
	v_add_f32_e32 v126, v18, v126
	v_exp_f32_e32 v22, v22
	v_sub_f32_e32 v23, v23, v134
	v_add_f32_e32 v126, v19, v126
	v_exp_f32_e32 v23, v23
	v_sub_f32_e32 v24, v24, v134
	v_add_f32_e32 v126, v20, v126
	v_exp_f32_e32 v24, v24
	v_sub_f32_e32 v25, v25, v134
	v_add_f32_e32 v126, v21, v126
	v_exp_f32_e32 v25, v25
	v_sub_f32_e32 v26, v26, v134
	v_add_f32_e32 v126, v22, v126
	v_exp_f32_e32 v26, v26
	v_sub_f32_e32 v27, v27, v134
	v_add_f32_e32 v126, v23, v126
	v_exp_f32_e32 v27, v27
	v_sub_f32_e32 v28, v28, v134
	v_add_f32_e32 v126, v24, v126
	v_exp_f32_e32 v28, v28
	v_sub_f32_e32 v29, v29, v134
	v_add_f32_e32 v126, v25, v126
	v_exp_f32_e32 v29, v29
	v_sub_f32_e32 v30, v30, v134
	v_add_f32_e32 v126, v26, v126
	v_exp_f32_e32 v30, v30
	v_sub_f32_e32 v31, v31, v134
	v_add_f32_e32 v126, v27, v126
	v_exp_f32_e32 v31, v31
	v_sub_f32_e32 v32, v32, v134
	v_add_f32_e32 v126, v28, v126
	v_exp_f32_e32 v32, v32
	v_sub_f32_e32 v33, v33, v134
	v_add_f32_e32 v126, v29, v126
	v_exp_f32_e32 v33, v33
	v_sub_f32_e32 v2, v2, v134
	v_add_f32_e32 v126, v30, v126
	v_exp_f32_e32 v2, v2
	v_sub_f32_e32 v3, v3, v134
	v_add_f32_e32 v126, v31, v126
	v_exp_f32_e32 v3, v3
	v_sub_f32_e32 v4, v4, v134
	v_add_f32_e32 v126, v32, v126
	v_exp_f32_e32 v4, v4
	v_sub_f32_e32 v5, v5, v134
	v_add_f32_e32 v126, v33, v126
	v_exp_f32_e32 v5, v5
	v_sub_f32_e32 v6, v6, v134
	v_add_f32_e32 v126, v2, v126
	v_exp_f32_e32 v6, v6
	v_sub_f32_e32 v7, v7, v134
	v_add_f32_e32 v126, v3, v126
	v_exp_f32_e32 v7, v7
	v_sub_f32_e32 v8, v8, v134
	v_add_f32_e32 v126, v4, v126
	v_exp_f32_e32 v8, v8
	v_sub_f32_e32 v9, v9, v134
	v_add_f32_e32 v126, v5, v126
	v_exp_f32_e32 v9, v9
	v_sub_f32_e32 v10, v10, v134
	v_add_f32_e32 v126, v6, v126
	v_exp_f32_e32 v10, v10
	v_sub_f32_e32 v11, v11, v134
	v_add_f32_e32 v126, v7, v126
	v_exp_f32_e32 v11, v11
	v_sub_f32_e32 v12, v12, v134
	v_add_f32_e32 v126, v8, v126
	v_exp_f32_e32 v12, v12
	v_sub_f32_e32 v13, v13, v134
	v_add_f32_e32 v126, v9, v126
	v_exp_f32_e32 v13, v13
	v_sub_f32_e32 v14, v14, v134
	v_add_f32_e32 v126, v10, v126
	v_exp_f32_e32 v14, v14
	v_sub_f32_e32 v15, v15, v134
	v_add_f32_e32 v126, v11, v126
	v_exp_f32_e32 v15, v15
	v_sub_f32_e32 v16, v16, v134
	v_add_f32_e32 v126, v12, v126
	v_exp_f32_e32 v16, v16
	v_sub_f32_e32 v17, v17, v134
	v_add_f32_e32 v126, v13, v126
	v_exp_f32_e32 v17, v17
	v_add_f32_e32 v126, v14, v126
	v_add_f32_e32 v126, v15, v126
	v_add_f32_e32 v126, v16, v126
	v_add_f32_e32 v126, v17, v126
	ds_bpermute_b32 v127, v133, v126
	s_and_saveexec_b64 s[48:49], vcc
	s_cbranch_execz .LBB0_489
	s_waitcnt lgkmcnt(0)
	v_add_f32_e32 v126, v126, v127
	v_rcp_f32_e32 v126, v126
	v_readlane_b32 s38, v251, 37
	s_nop 1
	v_lshl_add_u32 v127, v203, 2, s38
	ds_write_b32 v127, v126
	s_branch .LBB0_489
